# w_pg weight-conversion items: 16 LayerNorm-gain loads hoisted in front of one wait; c1/c2 column-sum loop pipelined (all W re-reads in flight, same summation order)
# speedup vs baseline: 1.0126x; 1.0126x over previous
; __device__ __forceinline__ void p0_transpose_item(const float* W, int K, int N, bf16* WT, float* scr, int item, int lane, const float* scale, const float* cb, float* c1, float* c2) {
;     const int nblk = N / 64, kb = item / nblk, nb = item % nblk, k0 = 64 * kb, n0 = 64 * nb;
;     const int lr = lane >> 4, lc = (lane & 15) * 4;
;     f32x4 v[16];
; #pragma unroll
;     for (int i = 0; i < 16; ++i) v[i] = *(const f32x4*)(W + (size_t)(k0 + 4 * i + lr) * N + n0 + lc);
; #pragma unroll
;     for (int i = 0; i < 16; ++i) { const int kk = 4 * i + lr; f32x4 w = v[i]; if (scale) w = w * scale[k0 + kk]; float* d = scr + kk * 65 + lc; d[0] = w[0]; d[1] = w[1]; d[2] = w[2]; d[3] = w[3]; }
.LBB0_26:
	s_andn2_b64 vcc, exec, s[4:5]
	s_cbranch_vccnz .LBB0_54
	s_lshl_b64 s[10:11], s[6:7], 24
	s_add_u32 s14, s16, s10
	s_addc_u32 s15, s17, s11
	s_lshl_b32 s4, s6, 11
	s_ashr_i32 s5, s4, 31
	v_readlane_b32 s64, v253, 18
	s_lshl_b64 s[8:9], s[4:5], 2
	v_readlane_b32 s74, v253, 28
	v_readlane_b32 s75, v253, 29
	s_add_u32 s12, s74, s8
	v_readlane_b32 s65, v253, 19
	s_addc_u32 s13, s75, s9
	s_lshl_b32 s63, s61, 1
	s_lshl_b32 s4, s61, 6
	s_add_i32 s63, s63, 0x1da00
	s_and_b32 s65, s4, 0x7c0
	s_and_b32 s64, s63, 0x1ffc0
	s_lshl_b32 s62, s65, 2
	s_add_u32 s4, s14, s62
	v_or_b32_e32 v64, s64, v80
	s_addc_u32 s5, s15, 0
	v_lshl_add_u64 v[0:1], s[4:5], 0, v[68:69]
	v_lshlrev_b32_e32 v2, 13, v64
	v_mov_b32_e32 v3, v69
	v_lshl_add_u64 v[0:1], v[0:1], 0, v[2:3]
	v_add_co_u32_e32 v2, vcc, s41, v0
	v_cndmask_b32_e64 v65, 0, 1, s[2:3]
	s_nop 0
	v_addc_co_u32_e32 v3, vcc, 0, v1, vcc
	global_load_dwordx4 v[56:59], v[0:1], off
	global_load_dwordx4 v[60:63], v[2:3], off
	v_add_co_u32_e32 v2, vcc, s42, v0
	v_cmp_ne_u32_e64 s[4:5], 1, v65
	s_nop 0
	v_addc_co_u32_e32 v3, vcc, 0, v1, vcc
	v_add_co_u32_e32 v4, vcc, s43, v0
	v_add_lshl_u32 v73, s64, v80, 2
	s_nop 0
	v_addc_co_u32_e32 v5, vcc, 0, v1, vcc
	global_load_dwordx4 v[48:51], v[2:3], off
	global_load_dwordx4 v[52:55], v[4:5], off
	v_add_co_u32_e32 v2, vcc, s44, v0
	v_readlane_b32 s66, v253, 20
	s_nop 0
	v_addc_co_u32_e32 v3, vcc, 0, v1, vcc
	v_add_co_u32_e32 v4, vcc, s45, v0
	v_readlane_b32 s67, v253, 21
	s_nop 0
	v_addc_co_u32_e32 v5, vcc, 0, v1, vcc
	global_load_dwordx4 v[40:43], v[2:3], off
	global_load_dwordx4 v[44:47], v[4:5], off
	v_add_co_u32_e32 v2, vcc, s46, v0
	v_readlane_b32 s68, v253, 22
	s_nop 0
	v_addc_co_u32_e32 v3, vcc, 0, v1, vcc
	v_add_co_u32_e32 v4, vcc, s47, v0
	v_readlane_b32 s69, v253, 23
	s_nop 0
	v_addc_co_u32_e32 v5, vcc, 0, v1, vcc
	global_load_dwordx4 v[32:35], v[2:3], off
	global_load_dwordx4 v[36:39], v[4:5], off
	v_add_co_u32_e32 v2, vcc, s48, v0
	v_readlane_b32 s70, v253, 24
	s_nop 0
	v_addc_co_u32_e32 v3, vcc, 0, v1, vcc
	v_add_co_u32_e32 v4, vcc, s49, v0
	v_readlane_b32 s71, v253, 25
	s_nop 0
	v_addc_co_u32_e32 v5, vcc, 0, v1, vcc
	global_load_dwordx4 v[24:27], v[2:3], off
	global_load_dwordx4 v[28:31], v[4:5], off
	v_add_co_u32_e32 v2, vcc, s50, v0
	v_readlane_b32 s72, v253, 26
	s_nop 0
	v_addc_co_u32_e32 v3, vcc, 0, v1, vcc
	v_add_co_u32_e32 v4, vcc, s51, v0
	v_readlane_b32 s73, v253, 27
	s_nop 0
	v_addc_co_u32_e32 v5, vcc, 0, v1, vcc
	global_load_dwordx4 v[16:19], v[2:3], off
	global_load_dwordx4 v[20:23], v[4:5], off
	v_add_co_u32_e32 v2, vcc, s52, v0
	v_readlane_b32 s76, v253, 30
	s_nop 0
	v_addc_co_u32_e32 v3, vcc, 0, v1, vcc
	v_add_co_u32_e32 v4, vcc, 0x68000, v0
	v_readlane_b32 s77, v253, 31
	s_nop 0
	v_addc_co_u32_e32 v5, vcc, 0, v1, vcc
	global_load_dwordx4 v[8:11], v[2:3], off
	global_load_dwordx4 v[12:15], v[4:5], off
	v_add_co_u32_e32 v2, vcc, 0x70000, v0
	v_readlane_b32 s78, v253, 32
	s_nop 0
	v_addc_co_u32_e32 v3, vcc, 0, v1, vcc
	v_add_co_u32_e32 v4, vcc, 0x78000, v0
	v_readlane_b32 s79, v253, 33
	s_nop 0
	v_addc_co_u32_e32 v5, vcc, 0, v1, vcc
	global_load_dwordx4 v[0:3], v[2:3], off
	s_nop 0
	global_load_dwordx4 v[4:7], v[4:5], off
	s_andn2_b64 vcc, exec, s[2:3]
	s_cbranch_vccnz .LBB0_59
	v_lshlrev_b32_e32 v64, 2, v64
	global_load_dword v64, v64, s[12:13]
	s_nop 0
	global_load_dword v124, v73, s[12:13] offset:16
	global_load_dword v126, v73, s[12:13] offset:32
	global_load_dword v128, v73, s[12:13] offset:48
	global_load_dword v130, v73, s[12:13] offset:64
	global_load_dword v132, v73, s[12:13] offset:80
	global_load_dword v134, v73, s[12:13] offset:96
	global_load_dword v136, v73, s[12:13] offset:112
	global_load_dword v138, v73, s[12:13] offset:128
	global_load_dword v140, v73, s[12:13] offset:144
	global_load_dword v142, v73, s[12:13] offset:160
	global_load_dword v144, v73, s[12:13] offset:176
	global_load_dword v146, v73, s[12:13] offset:192
	global_load_dword v148, v73, s[12:13] offset:208
	global_load_dword v150, v73, s[12:13] offset:224
	global_load_dword v152, v73, s[12:13] offset:240
	s_waitcnt vmcnt(0)
	v_pk_mul_f32 v[76:77], v[58:59], v[64:65] op_sel_hi:[1,0]
	v_pk_mul_f32 v[78:79], v[56:57], v[64:65] op_sel_hi:[1,0]
	v_pk_mul_f32 v[66:67], v[62:63], v[124:125] op_sel_hi:[1,0]
	v_pk_mul_f32 v[64:65], v[60:61], v[124:125] op_sel_hi:[1,0]
	s_cbranch_execnz .LBB0_30

; __device__ __forceinline__ void p0_transpose_item(const float* W, int K, int N, bf16* WT, float* scr, int item, int lane, const float* scale, const float* cb, float* c1, float* c2) {
;     ...
;     for (int i = 0; i < 16; ++i) { const int kk = 4 * i + lr; f32x4 w = v[i]; if (scale) w = w * scale[k0 + kk]; float* d = scr + kk * 65 + lc; d[0] = w[0]; d[1] = w[1]; d[2] = w[2]; d[3] = w[3]; }
.LBB0_30:
	s_and_b64 vcc, exec, s[4:5]
	ds_write2_b32 v81, v78, v79 offset1:1
	ds_write2_b32 v81, v76, v77 offset0:2 offset1:3
	ds_write2_b32 v122, v64, v65 offset1:1
	ds_write2_b32 v122, v66, v67 offset0:2 offset1:3
	s_cbranch_vccnz .LBB0_60
	v_pk_mul_f32 v[60:61], v[50:51], v[126:127] op_sel_hi:[1,0]
	v_pk_mul_f32 v[62:63], v[48:49], v[126:127] op_sel_hi:[1,0]
	v_pk_mul_f32 v[58:59], v[54:55], v[128:129] op_sel_hi:[1,0]
	v_pk_mul_f32 v[56:57], v[52:53], v[128:129] op_sel_hi:[1,0]
	s_cbranch_execnz .LBB0_33

; __device__ __forceinline__ void p0_transpose_item(const float* W, int K, int N, bf16* WT, float* scr, int item, int lane, const float* scale, const float* cb, float* c1, float* c2) {
;     ...
;     for (int i = 0; i < 16; ++i) { const int kk = 4 * i + lr; f32x4 w = v[i]; if (scale) w = w * scale[k0 + kk]; float* d = scr + kk * 65 + lc; d[0] = w[0]; d[1] = w[1]; d[2] = w[2]; d[3] = w[3]; }
.LBB0_33:
	s_waitcnt vmcnt(0)
	v_add_u32_e32 v48, 0x410, v122
	ds_write2_b32 v48, v62, v63 offset1:1
	v_add_u32_e32 v48, 0x418, v122
	ds_write2_b32 v48, v60, v61 offset1:1
	v_add_u32_e32 v48, 0x820, v122
	ds_write2_b32 v48, v56, v57 offset1:1
	v_add_u32_e32 v48, 0x828, v122
	s_and_b64 vcc, exec, s[4:5]
	ds_write2_b32 v48, v58, v59 offset1:1
	s_cbranch_vccnz .LBB0_61
	v_pk_mul_f32 v[52:53], v[42:43], v[130:131] op_sel_hi:[1,0]
	v_pk_mul_f32 v[54:55], v[40:41], v[130:131] op_sel_hi:[1,0]
	v_pk_mul_f32 v[50:51], v[46:47], v[132:133] op_sel_hi:[1,0]
	v_pk_mul_f32 v[48:49], v[44:45], v[132:133] op_sel_hi:[1,0]
	s_cbranch_execnz .LBB0_36

; __device__ __forceinline__ void p0_transpose_item(const float* W, int K, int N, bf16* WT, float* scr, int item, int lane, const float* scale, const float* cb, float* c1, float* c2) {
;     ...
;     for (int i = 0; i < 16; ++i) { const int kk = 4 * i + lr; f32x4 w = v[i]; if (scale) w = w * scale[k0 + kk]; float* d = scr + kk * 65 + lc; d[0] = w[0]; d[1] = w[1]; d[2] = w[2]; d[3] = w[3]; }
.LBB0_36:
	v_add_u32_e32 v40, 0xc30, v122
	ds_write2_b32 v40, v54, v55 offset1:1
	v_add_u32_e32 v40, 0xc38, v122
	ds_write2_b32 v40, v52, v53 offset1:1
	v_add_u32_e32 v40, 0x1040, v122
	ds_write2_b32 v40, v48, v49 offset1:1
	v_add_u32_e32 v40, 0x1048, v122
	s_and_b64 vcc, exec, s[4:5]
	ds_write2_b32 v40, v50, v51 offset1:1
	s_cbranch_vccnz .LBB0_62
	v_pk_mul_f32 v[44:45], v[34:35], v[134:135] op_sel_hi:[1,0]
	v_pk_mul_f32 v[46:47], v[32:33], v[134:135] op_sel_hi:[1,0]
	v_pk_mul_f32 v[42:43], v[38:39], v[136:137] op_sel_hi:[1,0]
	v_pk_mul_f32 v[40:41], v[36:37], v[136:137] op_sel_hi:[1,0]
	s_cbranch_execnz .LBB0_39

; __device__ __forceinline__ void p0_transpose_item(const float* W, int K, int N, bf16* WT, float* scr, int item, int lane, const float* scale, const float* cb, float* c1, float* c2) {
;     ...
;     for (int i = 0; i < 16; ++i) { const int kk = 4 * i + lr; f32x4 w = v[i]; if (scale) w = w * scale[k0 + kk]; float* d = scr + kk * 65 + lc; d[0] = w[0]; d[1] = w[1]; d[2] = w[2]; d[3] = w[3]; }
.LBB0_39:
	v_add_u32_e32 v32, 0x1450, v122
	ds_write2_b32 v32, v46, v47 offset1:1
	v_add_u32_e32 v32, 0x1458, v122
	ds_write2_b32 v32, v44, v45 offset1:1
	v_add_u32_e32 v32, 0x1860, v122
	ds_write2_b32 v32, v40, v41 offset1:1
	v_add_u32_e32 v32, 0x1868, v122
	s_and_b64 vcc, exec, s[4:5]
	ds_write2_b32 v32, v42, v43 offset1:1
	s_cbranch_vccnz .LBB0_63
	v_pk_mul_f32 v[36:37], v[26:27], v[138:139] op_sel_hi:[1,0]
	v_pk_mul_f32 v[38:39], v[24:25], v[138:139] op_sel_hi:[1,0]
	v_pk_mul_f32 v[34:35], v[30:31], v[140:141] op_sel_hi:[1,0]
	v_pk_mul_f32 v[32:33], v[28:29], v[140:141] op_sel_hi:[1,0]
	s_cbranch_execnz .LBB0_42

; __device__ __forceinline__ void p0_transpose_item(const float* W, int K, int N, bf16* WT, float* scr, int item, int lane, const float* scale, const float* cb, float* c1, float* c2) {
;     ...
;     for (int i = 0; i < 16; ++i) { const int kk = 4 * i + lr; f32x4 w = v[i]; if (scale) w = w * scale[k0 + kk]; float* d = scr + kk * 65 + lc; d[0] = w[0]; d[1] = w[1]; d[2] = w[2]; d[3] = w[3]; }
.LBB0_42:
	v_add_u32_e32 v24, 0x1c70, v122
	ds_write2_b32 v24, v38, v39 offset1:1
	v_add_u32_e32 v24, 0x1c78, v122
	ds_write2_b32 v24, v36, v37 offset1:1
	v_add_u32_e32 v24, 0x2080, v122
	ds_write2_b32 v24, v32, v33 offset1:1
	v_add_u32_e32 v24, 0x2088, v122
	s_and_b64 vcc, exec, s[4:5]
	ds_write2_b32 v24, v34, v35 offset1:1
	s_cbranch_vccnz .LBB0_64
	v_pk_mul_f32 v[28:29], v[18:19], v[142:143] op_sel_hi:[1,0]
	v_pk_mul_f32 v[30:31], v[16:17], v[142:143] op_sel_hi:[1,0]
	v_pk_mul_f32 v[26:27], v[22:23], v[144:145] op_sel_hi:[1,0]
	v_pk_mul_f32 v[24:25], v[20:21], v[144:145] op_sel_hi:[1,0]
	s_cbranch_execnz .LBB0_45

; __device__ __forceinline__ void p0_transpose_item(const float* W, int K, int N, bf16* WT, float* scr, int item, int lane, const float* scale, const float* cb, float* c1, float* c2) {
;     ...
;     for (int i = 0; i < 16; ++i) { const int kk = 4 * i + lr; f32x4 w = v[i]; if (scale) w = w * scale[k0 + kk]; float* d = scr + kk * 65 + lc; d[0] = w[0]; d[1] = w[1]; d[2] = w[2]; d[3] = w[3]; }
.LBB0_45:
	v_add_u32_e32 v16, 0x2490, v122
	ds_write2_b32 v16, v30, v31 offset1:1
	v_add_u32_e32 v16, 0x2498, v122
	ds_write2_b32 v16, v28, v29 offset1:1
	v_add_u32_e32 v16, 0x28a0, v122
	ds_write2_b32 v16, v24, v25 offset1:1
	v_add_u32_e32 v16, 0x28a8, v122
	s_and_b64 vcc, exec, s[4:5]
	ds_write2_b32 v16, v26, v27 offset1:1
	s_cbranch_vccnz .LBB0_65
	v_pk_mul_f32 v[20:21], v[10:11], v[146:147] op_sel_hi:[1,0]
	v_pk_mul_f32 v[22:23], v[8:9], v[146:147] op_sel_hi:[1,0]
	v_pk_mul_f32 v[18:19], v[14:15], v[148:149] op_sel_hi:[1,0]
	v_pk_mul_f32 v[16:17], v[12:13], v[148:149] op_sel_hi:[1,0]
	s_cbranch_execnz .LBB0_48

; __device__ __forceinline__ void p0_transpose_item(const float* W, int K, int N, bf16* WT, float* scr, int item, int lane, const float* scale, const float* cb, float* c1, float* c2) {
;     ...
;     for (int i = 0; i < 16; ++i) { const int kk = 4 * i + lr; f32x4 w = v[i]; if (scale) w = w * scale[k0 + kk]; float* d = scr + kk * 65 + lc; d[0] = w[0]; d[1] = w[1]; d[2] = w[2]; d[3] = w[3]; }
.LBB0_48:
	v_add_u32_e32 v8, 0x2cb0, v122
	ds_write2_b32 v8, v22, v23 offset1:1
	v_add_u32_e32 v8, 0x2cb8, v122
	ds_write2_b32 v8, v20, v21 offset1:1
	v_add_u32_e32 v8, 0x30c0, v122
	ds_write2_b32 v8, v16, v17 offset1:1
	v_add_u32_e32 v8, 0x30c8, v122
	s_and_b64 vcc, exec, s[4:5]
	ds_write2_b32 v8, v18, v19 offset1:1
	s_cbranch_vccnz .LBB0_66
	v_pk_mul_f32 v[12:13], v[2:3], v[150:151] op_sel_hi:[1,0]
	v_pk_mul_f32 v[14:15], v[0:1], v[150:151] op_sel_hi:[1,0]
	v_pk_mul_f32 v[10:11], v[6:7], v[152:153] op_sel_hi:[1,0]
	v_pk_mul_f32 v[8:9], v[4:5], v[152:153] op_sel_hi:[1,0]
	s_cbranch_execnz .LBB0_51

; #define LDS_WAIT() asm volatile("s_waitcnt lgkmcnt(0)" ::: "memory")
; __device__ __forceinline__ unsigned pk2(float lo, float hi) { unsigned r; asm("v_cvt_pk_bf16_f32 %0, %1, %2" : "=v"(r) : "v"(lo), "v"(hi)); return r; }
; __device__ __forceinline__ void p0_transpose_item(const float* W, int K, int N, bf16* WT, float* scr, int item, int lane, const float* scale, const float* cb, float* c1, float* c2) {
;     ...
;     for (int i = 0; i < 16; ++i) { const int kk = 4 * i + lr; f32x4 w = v[i]; if (scale) w = w * scale[k0 + kk]; float* d = scr + kk * 65 + lc; d[0] = w[0]; d[1] = w[1]; d[2] = w[2]; d[3] = w[3]; }
;     LDS_WAIT(); asm volatile("" ::: "memory");
;     const int c = lane & 7;
; #pragma unroll
;     for (int j = 0; j < 8; ++j) { const int n = (lane >> 3) + 8 * j; const float* sp = scr + (8 * c) * 65 + n;
;         v4u o; o.x = pk2(sp[0 * 65], sp[1 * 65]); o.y = pk2(sp[2 * 65], sp[3 * 65]); o.z = pk2(sp[4 * 65], sp[5 * 65]); o.w = pk2(sp[6 * 65], sp[7 * 65]);
;         *(v4u*)(WT + (size_t)(n0 + n) * K + k0 + 8 * c) = o; }
.LBB0_51:
	v_add_u32_e32 v0, 0x34d0, v122
	ds_write2_b32 v0, v14, v15 offset1:1
	v_add_u32_e32 v0, 0x34d8, v122
	ds_write2_b32 v0, v12, v13 offset1:1
	v_add_u32_e32 v0, 0x38e0, v122
	ds_write2_b32 v0, v8, v9 offset1:1
	v_add_u32_e32 v0, 0x38e8, v122
	ds_write2_b32 v0, v10, v11 offset1:1
	s_lshl_b64 s[4:5], s[6:7], 22
	s_waitcnt lgkmcnt(0)
	s_lshl_b64 s[4:5], s[4:5], 1
	s_add_u32 s4, s30, s4
	ds_read_b32 v0, v83
	ds_read_b32 v1, v83 offset:260
	ds_read_b32 v2, v83 offset:520
	ds_read_b32 v3, v83 offset:780
	ds_read_b32 v6, v83 offset:1040
	ds_read_b32 v7, v83 offset:1300
	ds_read_b32 v8, v83 offset:1560
	ds_read_b32 v9, v83 offset:1820
	s_addc_u32 s5, s31, s5
	s_lshl_b32 s7, s64, 1
	s_add_u32 s4, s4, s7
	s_addc_u32 s5, s5, 0
	v_mov_b32_e32 v75, v69
	s_waitcnt lgkmcnt(0)
	v_cvt_pk_bf16_f32 v0, v0, v1
	v_cvt_pk_bf16_f32 v1, v2, v3
	v_cvt_pk_bf16_f32 v2, v6, v7
	v_or_b32_e32 v6, s65, v82
	v_lshl_add_u64 v[4:5], s[4:5], 0, v[74:75]
	v_lshlrev_b32_e32 v6, 12, v6
	v_mov_b32_e32 v7, v69
	v_lshl_add_u64 v[6:7], v[4:5], 0, v[6:7]
	v_cvt_pk_bf16_f32 v3, v8, v9
	global_store_dwordx4 v[6:7], v[0:3], off
	ds_read_b32 v0, v83 offset:32
	ds_read_b32 v1, v83 offset:292
	ds_read_b32 v2, v83 offset:552
	ds_read_b32 v3, v83 offset:812
	ds_read_b32 v6, v83 offset:1072
	ds_read_b32 v7, v83 offset:1332
	ds_read_b32 v8, v83 offset:1592
	ds_read_b32 v9, v83 offset:1852
	s_waitcnt lgkmcnt(0)
	v_cvt_pk_bf16_f32 v0, v0, v1
	v_cvt_pk_bf16_f32 v1, v2, v3
	v_cvt_pk_bf16_f32 v2, v6, v7
	v_or_b32_e32 v6, s65, v84
	v_lshlrev_b32_e32 v6, 12, v6
	v_mov_b32_e32 v7, v69
	v_lshl_add_u64 v[6:7], v[4:5], 0, v[6:7]
	v_cvt_pk_bf16_f32 v3, v8, v9
	global_store_dwordx4 v[6:7], v[0:3], off
	ds_read_b32 v0, v83 offset:64
	ds_read_b32 v1, v83 offset:324
	ds_read_b32 v2, v83 offset:584
	ds_read_b32 v3, v83 offset:844
	ds_read_b32 v6, v83 offset:1104
	ds_read_b32 v7, v83 offset:1364
	ds_read_b32 v8, v83 offset:1624
	ds_read_b32 v9, v83 offset:1884
	s_waitcnt lgkmcnt(0)
	v_cvt_pk_bf16_f32 v0, v0, v1
	v_cvt_pk_bf16_f32 v1, v2, v3
	v_cvt_pk_bf16_f32 v2, v6, v7
	v_or_b32_e32 v6, s65, v85
	v_lshlrev_b32_e32 v6, 12, v6
	v_mov_b32_e32 v7, v69
	v_lshl_add_u64 v[6:7], v[4:5], 0, v[6:7]
	v_cvt_pk_bf16_f32 v3, v8, v9
	global_store_dwordx4 v[6:7], v[0:3], off
	ds_read_b32 v0, v83 offset:96
	ds_read_b32 v1, v83 offset:356
	ds_read_b32 v2, v83 offset:616
	ds_read_b32 v3, v83 offset:876
	ds_read_b32 v6, v83 offset:1136
	ds_read_b32 v7, v83 offset:1396
	ds_read_b32 v8, v83 offset:1656
	ds_read_b32 v9, v83 offset:1916
	s_waitcnt lgkmcnt(0)
	v_cvt_pk_bf16_f32 v0, v0, v1
	v_cvt_pk_bf16_f32 v1, v2, v3
	v_cvt_pk_bf16_f32 v2, v6, v7
	v_or_b32_e32 v6, s65, v86
	v_lshlrev_b32_e32 v6, 12, v6
	v_mov_b32_e32 v7, v69
	v_lshl_add_u64 v[6:7], v[4:5], 0, v[6:7]
	v_cvt_pk_bf16_f32 v3, v8, v9
	global_store_dwordx4 v[6:7], v[0:3], off
	ds_read_b32 v0, v83 offset:128
	ds_read_b32 v1, v83 offset:388
	ds_read_b32 v2, v83 offset:648
	ds_read_b32 v3, v83 offset:908
	ds_read_b32 v6, v83 offset:1168
	ds_read_b32 v7, v83 offset:1428
	ds_read_b32 v8, v83 offset:1688
	ds_read_b32 v9, v83 offset:1948
	s_waitcnt lgkmcnt(0)
	v_cvt_pk_bf16_f32 v0, v0, v1
	v_cvt_pk_bf16_f32 v1, v2, v3
	v_cvt_pk_bf16_f32 v2, v6, v7
	v_or_b32_e32 v6, s65, v87
	v_lshlrev_b32_e32 v6, 12, v6
	v_mov_b32_e32 v7, v69
	v_lshl_add_u64 v[6:7], v[4:5], 0, v[6:7]
	v_cvt_pk_bf16_f32 v3, v8, v9
	global_store_dwordx4 v[6:7], v[0:3], off
	ds_read_b32 v0, v83 offset:160
	ds_read_b32 v1, v83 offset:420
	ds_read_b32 v2, v83 offset:680
	ds_read_b32 v3, v83 offset:940
	ds_read_b32 v6, v83 offset:1200
	ds_read_b32 v7, v83 offset:1460
	ds_read_b32 v8, v83 offset:1720
	ds_read_b32 v9, v83 offset:1980
	s_waitcnt lgkmcnt(0)
	v_cvt_pk_bf16_f32 v0, v0, v1
	v_cvt_pk_bf16_f32 v1, v2, v3
	v_cvt_pk_bf16_f32 v2, v6, v7
	v_or_b32_e32 v6, s65, v88
	v_lshlrev_b32_e32 v6, 12, v6
	v_mov_b32_e32 v7, v69
	v_lshl_add_u64 v[6:7], v[4:5], 0, v[6:7]
	v_cvt_pk_bf16_f32 v3, v8, v9
	global_store_dwordx4 v[6:7], v[0:3], off
	ds_read_b32 v0, v83 offset:192
	ds_read_b32 v1, v83 offset:452
	ds_read_b32 v2, v83 offset:712
	ds_read_b32 v3, v83 offset:972
	ds_read_b32 v6, v83 offset:1232
	ds_read_b32 v7, v83 offset:1492
	ds_read_b32 v8, v83 offset:1752
	ds_read_b32 v9, v83 offset:2012
	s_waitcnt lgkmcnt(0)
	v_cvt_pk_bf16_f32 v0, v0, v1
	v_cvt_pk_bf16_f32 v1, v2, v3
	v_cvt_pk_bf16_f32 v2, v6, v7
	v_or_b32_e32 v6, s65, v89
	v_lshlrev_b32_e32 v6, 12, v6
	v_mov_b32_e32 v7, v69
	v_lshl_add_u64 v[6:7], v[4:5], 0, v[6:7]
	v_cvt_pk_bf16_f32 v3, v8, v9
	global_store_dwordx4 v[6:7], v[0:3], off
	ds_read_b32 v0, v83 offset:224
	ds_read_b32 v1, v83 offset:484
	ds_read_b32 v2, v83 offset:744
	ds_read_b32 v3, v83 offset:1004
	ds_read_b32 v6, v83 offset:1264
	ds_read_b32 v7, v83 offset:1524
	ds_read_b32 v8, v83 offset:1784
	ds_read_b32 v9, v83 offset:2044
	s_lshl_b32 s4, s63, 13
	s_and_b32 s4, s4, 0x3ff80000
	s_add_u32 s4, s10, s4
	s_waitcnt lgkmcnt(0)
; __device__ __forceinline__ unsigned pk2(float lo, float hi) { unsigned r; asm("v_cvt_pk_bf16_f32 %0, %1, %2" : "=v"(r) : "v"(lo), "v"(hi)); return r; }
; __device__ __forceinline__ unsigned f2bf(float f) { return pk2(f, 0.f) & 0xffffu; }
; __device__ __forceinline__ void p0_transpose_item(const float* W, int K, int N, bf16* WT, float* scr, int item, int lane, const float* scale, const float* cb, float* c1, float* c2) {
;     ...
;     for (int j = 0; j < 8; ++j) { const int n = (lane >> 3) + 8 * j; const float* sp = scr + (8 * c) * 65 + n;
;         v4u o; o.x = pk2(sp[0 * 65], sp[1 * 65]); o.y = pk2(sp[2 * 65], sp[3 * 65]); o.z = pk2(sp[4 * 65], sp[5 * 65]); o.w = pk2(sp[6 * 65], sp[7 * 65]);
;         *(v4u*)(WT + (size_t)(n0 + n) * K + k0 + 8 * c) = o; }
;     if (c1) { float a1 = 0.f, a2 = 0.f;
;         for (int kk = 0; kk < 64; ++kk) { a1 += __uint_as_float(f2bf(scr[kk * 65 + lane]) << 16); a2 += cb[k0 + kk] * W[(size_t)(k0 + kk) * N + n0 + lane]; }
	v_cvt_pk_bf16_f32 v0, v0, v1
	v_cvt_pk_bf16_f32 v1, v2, v3
	v_cvt_pk_bf16_f32 v2, v6, v7
	v_or_b32_e32 v6, s65, v90
	s_addc_u32 s5, s11, 0
	s_and_b32 s7, s61, 31
	v_lshlrev_b32_e32 v6, 12, v6
	v_mov_b32_e32 v7, v69
	s_lshl_b32 s7, s7, 8
	v_lshl_add_u64 v[4:5], v[4:5], 0, v[6:7]
	s_or_b32 s4, s4, s7
	v_cvt_pk_bf16_f32 v3, v8, v9
	global_store_dwordx4 v[4:5], v[0:3], off
	v_mov_b32_e32 v4, v91
	s_nop 0
	v_lshl_add_u64 v[0:1], v[70:71], 0, s[4:5]
	s_lshl_b32 s4, s64, 2
	v_readlane_b32 s64, v253, 18
	v_readlane_b32 s76, v253, 30
	v_readlane_b32 s77, v253, 31
	s_add_u32 s7, s76, s4
	s_addc_u32 s12, s77, 0
	s_lshl_b32 s4, s63, 2
	s_and_b32 s4, s4, 0x7ff00
	s_add_u32 s13, s76, s4
	v_mov_b32_e32 v2, 0
	s_addc_u32 s14, s77, 0
	s_mov_b64 s[4:5], 0
	v_mov_b32_e32 v3, v2
	v_readlane_b32 s65, v253, 19
	v_readlane_b32 s66, v253, 20
	v_readlane_b32 s67, v253, 21
	v_readlane_b32 s68, v253, 22
	v_readlane_b32 s69, v253, 23
	v_readlane_b32 s70, v253, 24
	v_readlane_b32 s71, v253, 25
	v_readlane_b32 s72, v253, 26
	v_readlane_b32 s73, v253, 27
	v_readlane_b32 s74, v253, 28
	v_readlane_b32 s75, v253, 29
	v_readlane_b32 s78, v253, 32
	v_readlane_b32 s79, v253, 33
	s_add_u32 s10, s13, s8
	s_addc_u32 s11, s14, s9
	v_and_b32_e32 v154, 63, v252
	v_lshlrev_b32_e32 v154, 2, v154
	v_mov_b32_e32 v156, v0
	v_mov_b32_e32 v157, v1
	global_load_dword v155, v154, s[10:11]
	s_mov_b64 s[10:11], 0x2000
	global_load_dword v158, v[156:157], off
	v_lshl_add_u64 v[156:157], v[156:157], 0, s[10:11]
	global_load_dword v159, v[156:157], off
	v_lshl_add_u64 v[156:157], v[156:157], 0, s[10:11]
	global_load_dword v160, v[156:157], off
	v_lshl_add_u64 v[156:157], v[156:157], 0, s[10:11]
	global_load_dword v161, v[156:157], off
	v_lshl_add_u64 v[156:157], v[156:157], 0, s[10:11]
	global_load_dword v162, v[156:157], off
	v_lshl_add_u64 v[156:157], v[156:157], 0, s[10:11]
	global_load_dword v163, v[156:157], off
	v_lshl_add_u64 v[156:157], v[156:157], 0, s[10:11]
	global_load_dword v164, v[156:157], off
	v_lshl_add_u64 v[156:157], v[156:157], 0, s[10:11]
	global_load_dword v165, v[156:157], off
	v_lshl_add_u64 v[156:157], v[156:157], 0, s[10:11]
	global_load_dword v166, v[156:157], off
	v_lshl_add_u64 v[156:157], v[156:157], 0, s[10:11]
	global_load_dword v167, v[156:157], off
	v_lshl_add_u64 v[156:157], v[156:157], 0, s[10:11]
	global_load_dword v168, v[156:157], off
	v_lshl_add_u64 v[156:157], v[156:157], 0, s[10:11]
	global_load_dword v174, v[156:157], off
	v_lshl_add_u64 v[156:157], v[156:157], 0, s[10:11]
	global_load_dword v175, v[156:157], off
	v_lshl_add_u64 v[156:157], v[156:157], 0, s[10:11]
	global_load_dword v176, v[156:157], off
	v_lshl_add_u64 v[156:157], v[156:157], 0, s[10:11]
	global_load_dword v177, v[156:157], off
	v_lshl_add_u64 v[156:157], v[156:157], 0, s[10:11]
	global_load_dword v178, v[156:157], off
	v_lshl_add_u64 v[156:157], v[156:157], 0, s[10:11]
	global_load_dword v179, v[156:157], off
	v_lshl_add_u64 v[156:157], v[156:157], 0, s[10:11]
	global_load_dword v180, v[156:157], off
	v_lshl_add_u64 v[156:157], v[156:157], 0, s[10:11]
	global_load_dword v181, v[156:157], off
	v_lshl_add_u64 v[156:157], v[156:157], 0, s[10:11]
	global_load_dword v182, v[156:157], off
	v_lshl_add_u64 v[156:157], v[156:157], 0, s[10:11]
	global_load_dword v183, v[156:157], off
	v_lshl_add_u64 v[156:157], v[156:157], 0, s[10:11]
	global_load_dword v184, v[156:157], off
	v_lshl_add_u64 v[156:157], v[156:157], 0, s[10:11]
	global_load_dword v185, v[156:157], off
	v_lshl_add_u64 v[156:157], v[156:157], 0, s[10:11]
	global_load_dword v186, v[156:157], off
	v_lshl_add_u64 v[156:157], v[156:157], 0, s[10:11]
	global_load_dword v187, v[156:157], off
	v_lshl_add_u64 v[156:157], v[156:157], 0, s[10:11]
	global_load_dword v188, v[156:157], off
	v_lshl_add_u64 v[156:157], v[156:157], 0, s[10:11]
	global_load_dword v189, v[156:157], off
	v_lshl_add_u64 v[156:157], v[156:157], 0, s[10:11]
	global_load_dword v190, v[156:157], off
	v_lshl_add_u64 v[156:157], v[156:157], 0, s[10:11]
	global_load_dword v191, v[156:157], off
	v_lshl_add_u64 v[156:157], v[156:157], 0, s[10:11]
	global_load_dword v192, v[156:157], off
	v_lshl_add_u64 v[156:157], v[156:157], 0, s[10:11]
	global_load_dword v193, v[156:157], off
	v_lshl_add_u64 v[156:157], v[156:157], 0, s[10:11]
	global_load_dword v194, v[156:157], off
	v_lshl_add_u64 v[156:157], v[156:157], 0, s[10:11]
	global_load_dword v195, v[156:157], off
	v_lshl_add_u64 v[156:157], v[156:157], 0, s[10:11]
	global_load_dword v196, v[156:157], off
	v_lshl_add_u64 v[156:157], v[156:157], 0, s[10:11]
	global_load_dword v197, v[156:157], off
	v_lshl_add_u64 v[156:157], v[156:157], 0, s[10:11]
	global_load_dword v198, v[156:157], off
	v_lshl_add_u64 v[156:157], v[156:157], 0, s[10:11]
	global_load_dword v199, v[156:157], off
	v_lshl_add_u64 v[156:157], v[156:157], 0, s[10:11]
	global_load_dword v200, v[156:157], off
	v_lshl_add_u64 v[156:157], v[156:157], 0, s[10:11]
	global_load_dword v201, v[156:157], off
	v_lshl_add_u64 v[156:157], v[156:157], 0, s[10:11]
	global_load_dword v202, v[156:157], off
	v_lshl_add_u64 v[156:157], v[156:157], 0, s[10:11]
	global_load_dword v203, v[156:157], off
	v_lshl_add_u64 v[156:157], v[156:157], 0, s[10:11]
	global_load_dword v204, v[156:157], off
	v_lshl_add_u64 v[156:157], v[156:157], 0, s[10:11]
	global_load_dword v205, v[156:157], off
	v_lshl_add_u64 v[156:157], v[156:157], 0, s[10:11]
	global_load_dword v206, v[156:157], off
	v_lshl_add_u64 v[156:157], v[156:157], 0, s[10:11]
	global_load_dword v207, v[156:157], off
	v_lshl_add_u64 v[156:157], v[156:157], 0, s[10:11]
	global_load_dword v208, v[156:157], off
	v_lshl_add_u64 v[156:157], v[156:157], 0, s[10:11]
	global_load_dword v209, v[156:157], off
	v_lshl_add_u64 v[156:157], v[156:157], 0, s[10:11]
	global_load_dword v210, v[156:157], off
	v_lshl_add_u64 v[156:157], v[156:157], 0, s[10:11]
	v_add_u32_e32 v25, 0x400, v4
	ds_read2_b32 v[8:9], v4 offset1:65
	ds_read2_b32 v[10:11], v4 offset0:130 offset1:195
	ds_read2_b32 v[12:13], v25 offset0:4 offset1:69
	ds_read2_b32 v[14:15], v25 offset0:134 offset1:199
	v_add_u32_e32 v24, 0x820, v4
	v_add_u32_e32 v25, 0xc20, v4
	ds_read2_b32 v[16:17], v24 offset1:65
	ds_read2_b32 v[18:19], v24 offset0:130 offset1:195
	ds_read2_b32 v[20:21], v25 offset0:4 offset1:69
	ds_read2_b32 v[22:23], v25 offset0:134 offset1:199
	s_waitcnt vmcnt(32)
; __device__ __forceinline__ unsigned f2bf(float f) { return pk2(f, 0.f) & 0xffffu; }
; __device__ __forceinline__ void p0_transpose_item(const float* W, int K, int N, bf16* WT, float* scr, int item, int lane, const float* scale, const float* cb, float* c1, float* c2) {
;     ...
;     if (c1) { float a1 = 0.f, a2 = 0.f;
;         for (int kk = 0; kk < 64; ++kk) { a1 += __uint_as_float(f2bf(scr[kk * 65 + lane]) << 16); a2 += cb[k0 + kk] * W[(size_t)(k0 + kk) * N + n0 + lane]; }
	s_waitcnt lgkmcnt(4)
	v_cvt_pk_bf16_f32 v26, v8, v69
	v_readlane_b32 vcc_lo, v155, 0
	v_lshlrev_b32_e32 v26, 16, v26
	v_mul_f32_e32 v27, vcc_lo, v158
	v_add_f32_e32 v3, v3, v26
	v_add_f32_e32 v2, v2, v27
	v_cvt_pk_bf16_f32 v28, v9, v69
	v_readlane_b32 vcc_hi, v155, 1
	v_lshlrev_b32_e32 v28, 16, v28
	v_mul_f32_e32 v29, vcc_hi, v159
	v_add_f32_e32 v3, v3, v28
	v_add_f32_e32 v2, v2, v29
	v_cvt_pk_bf16_f32 v26, v10, v69
	v_readlane_b32 vcc_lo, v155, 2
	v_lshlrev_b32_e32 v26, 16, v26
	v_mul_f32_e32 v27, vcc_lo, v160
	v_add_f32_e32 v3, v3, v26
	v_add_f32_e32 v2, v2, v27
	v_cvt_pk_bf16_f32 v28, v11, v69
	v_readlane_b32 vcc_hi, v155, 3
	v_lshlrev_b32_e32 v28, 16, v28
	v_mul_f32_e32 v29, vcc_hi, v161
	v_add_f32_e32 v3, v3, v28
	v_add_f32_e32 v2, v2, v29
	v_cvt_pk_bf16_f32 v26, v12, v69
	v_readlane_b32 vcc_lo, v155, 4
	v_lshlrev_b32_e32 v26, 16, v26
	v_mul_f32_e32 v27, vcc_lo, v162
	v_add_f32_e32 v3, v3, v26
	v_add_f32_e32 v2, v2, v27
	v_cvt_pk_bf16_f32 v28, v13, v69
	v_readlane_b32 vcc_hi, v155, 5
	v_lshlrev_b32_e32 v28, 16, v28
	v_mul_f32_e32 v29, vcc_hi, v163
	v_add_f32_e32 v3, v3, v28
	v_add_f32_e32 v2, v2, v29
	v_cvt_pk_bf16_f32 v26, v14, v69
	v_readlane_b32 vcc_lo, v155, 6
	v_lshlrev_b32_e32 v26, 16, v26
	v_mul_f32_e32 v27, vcc_lo, v164
	v_add_f32_e32 v3, v3, v26
	v_add_f32_e32 v2, v2, v27
	v_cvt_pk_bf16_f32 v28, v15, v69
	v_readlane_b32 vcc_hi, v155, 7
	v_lshlrev_b32_e32 v28, 16, v28
	v_mul_f32_e32 v29, vcc_hi, v165
	v_add_f32_e32 v3, v3, v28
	v_add_f32_e32 v2, v2, v29
	v_add_u32_e32 v24, 0x1040, v4
	v_add_u32_e32 v25, 0x1440, v4
	ds_read2_b32 v[8:9], v24 offset1:65
	ds_read2_b32 v[10:11], v24 offset0:130 offset1:195
	ds_read2_b32 v[12:13], v25 offset0:4 offset1:69
	ds_read2_b32 v[14:15], v25 offset0:134 offset1:199
	s_waitcnt lgkmcnt(4)
	v_cvt_pk_bf16_f32 v26, v16, v69
	v_readlane_b32 vcc_lo, v155, 8
	v_lshlrev_b32_e32 v26, 16, v26
	v_mul_f32_e32 v27, vcc_lo, v166
	v_add_f32_e32 v3, v3, v26
	v_add_f32_e32 v2, v2, v27
	v_cvt_pk_bf16_f32 v28, v17, v69
	v_readlane_b32 vcc_hi, v155, 9
	v_lshlrev_b32_e32 v28, 16, v28
	v_mul_f32_e32 v29, vcc_hi, v167
	v_add_f32_e32 v3, v3, v28
	v_add_f32_e32 v2, v2, v29
	v_cvt_pk_bf16_f32 v26, v18, v69
	v_readlane_b32 vcc_lo, v155, 10
	v_lshlrev_b32_e32 v26, 16, v26
	v_mul_f32_e32 v27, vcc_lo, v168
	v_add_f32_e32 v3, v3, v26
	v_add_f32_e32 v2, v2, v27
	v_cvt_pk_bf16_f32 v28, v19, v69
	v_readlane_b32 vcc_hi, v155, 11
	v_lshlrev_b32_e32 v28, 16, v28
	v_mul_f32_e32 v29, vcc_hi, v174
	v_add_f32_e32 v3, v3, v28
	v_add_f32_e32 v2, v2, v29
	v_cvt_pk_bf16_f32 v26, v20, v69
	v_readlane_b32 vcc_lo, v155, 12
	v_lshlrev_b32_e32 v26, 16, v26
	v_mul_f32_e32 v27, vcc_lo, v175
	v_add_f32_e32 v3, v3, v26
	v_add_f32_e32 v2, v2, v27
	v_cvt_pk_bf16_f32 v28, v21, v69
	v_readlane_b32 vcc_hi, v155, 13
	v_lshlrev_b32_e32 v28, 16, v28
	v_mul_f32_e32 v29, vcc_hi, v176
	v_add_f32_e32 v3, v3, v28
	v_add_f32_e32 v2, v2, v29
	v_cvt_pk_bf16_f32 v26, v22, v69
	v_readlane_b32 vcc_lo, v155, 14
	v_lshlrev_b32_e32 v26, 16, v26
	v_mul_f32_e32 v27, vcc_lo, v177
	v_add_f32_e32 v3, v3, v26
	v_add_f32_e32 v2, v2, v27
	v_cvt_pk_bf16_f32 v28, v23, v69
	v_readlane_b32 vcc_hi, v155, 15
	v_lshlrev_b32_e32 v28, 16, v28
	v_mul_f32_e32 v29, vcc_hi, v178
	v_add_f32_e32 v3, v3, v28
	v_add_f32_e32 v2, v2, v29
	global_load_dword v211, v[156:157], off
	v_lshl_add_u64 v[156:157], v[156:157], 0, s[10:11]
	global_load_dword v212, v[156:157], off
	v_lshl_add_u64 v[156:157], v[156:157], 0, s[10:11]
	global_load_dword v213, v[156:157], off
	v_lshl_add_u64 v[156:157], v[156:157], 0, s[10:11]
	global_load_dword v224, v[156:157], off
	v_lshl_add_u64 v[156:157], v[156:157], 0, s[10:11]
	global_load_dword v225, v[156:157], off
	v_lshl_add_u64 v[156:157], v[156:157], 0, s[10:11]
	global_load_dword v226, v[156:157], off
	v_lshl_add_u64 v[156:157], v[156:157], 0, s[10:11]
	global_load_dword v227, v[156:157], off
	v_lshl_add_u64 v[156:157], v[156:157], 0, s[10:11]
	global_load_dword v228, v[156:157], off
	v_lshl_add_u64 v[156:157], v[156:157], 0, s[10:11]
	global_load_dword v229, v[156:157], off
	v_lshl_add_u64 v[156:157], v[156:157], 0, s[10:11]
	global_load_dword v230, v[156:157], off
	v_lshl_add_u64 v[156:157], v[156:157], 0, s[10:11]
	global_load_dword v231, v[156:157], off
	v_lshl_add_u64 v[156:157], v[156:157], 0, s[10:11]
	global_load_dword v232, v[156:157], off
	v_lshl_add_u64 v[156:157], v[156:157], 0, s[10:11]
	global_load_dword v233, v[156:157], off
	v_lshl_add_u64 v[156:157], v[156:157], 0, s[10:11]
	global_load_dword v234, v[156:157], off
	v_lshl_add_u64 v[156:157], v[156:157], 0, s[10:11]
	global_load_dword v235, v[156:157], off
	v_lshl_add_u64 v[156:157], v[156:157], 0, s[10:11]
	global_load_dword v236, v[156:157], off
	v_lshl_add_u64 v[156:157], v[156:157], 0, s[10:11]
	v_add_u32_e32 v24, 0x1860, v4
	v_add_u32_e32 v25, 0x1c60, v4
	ds_read2_b32 v[16:17], v24 offset1:65
	ds_read2_b32 v[18:19], v24 offset0:130 offset1:195
	ds_read2_b32 v[20:21], v25 offset0:4 offset1:69
	ds_read2_b32 v[22:23], v25 offset0:134 offset1:199
	s_waitcnt vmcnt(32)
	s_waitcnt lgkmcnt(4)
; __device__ __forceinline__ unsigned f2bf(float f) { return pk2(f, 0.f) & 0xffffu; }
; __device__ __forceinline__ void p0_transpose_item(const float* W, int K, int N, bf16* WT, float* scr, int item, int lane, const float* scale, const float* cb, float* c1, float* c2) {
;     ...
;     if (c1) { float a1 = 0.f, a2 = 0.f;
;         for (int kk = 0; kk < 64; ++kk) { a1 += __uint_as_float(f2bf(scr[kk * 65 + lane]) << 16); a2 += cb[k0 + kk] * W[(size_t)(k0 + kk) * N + n0 + lane]; }
	v_cvt_pk_bf16_f32 v26, v8, v69
	v_readlane_b32 vcc_lo, v155, 16
	v_lshlrev_b32_e32 v26, 16, v26
	v_mul_f32_e32 v27, vcc_lo, v179
	v_add_f32_e32 v3, v3, v26
	v_add_f32_e32 v2, v2, v27
	v_cvt_pk_bf16_f32 v28, v9, v69
	v_readlane_b32 vcc_hi, v155, 17
	v_lshlrev_b32_e32 v28, 16, v28
	v_mul_f32_e32 v29, vcc_hi, v180
	v_add_f32_e32 v3, v3, v28
	v_add_f32_e32 v2, v2, v29
	v_cvt_pk_bf16_f32 v26, v10, v69
	v_readlane_b32 vcc_lo, v155, 18
	v_lshlrev_b32_e32 v26, 16, v26
	v_mul_f32_e32 v27, vcc_lo, v181
	v_add_f32_e32 v3, v3, v26
	v_add_f32_e32 v2, v2, v27
	v_cvt_pk_bf16_f32 v28, v11, v69
	v_readlane_b32 vcc_hi, v155, 19
	v_lshlrev_b32_e32 v28, 16, v28
	v_mul_f32_e32 v29, vcc_hi, v182
	v_add_f32_e32 v3, v3, v28
	v_add_f32_e32 v2, v2, v29
	v_cvt_pk_bf16_f32 v26, v12, v69
	v_readlane_b32 vcc_lo, v155, 20
	v_lshlrev_b32_e32 v26, 16, v26
	v_mul_f32_e32 v27, vcc_lo, v183
	v_add_f32_e32 v3, v3, v26
	v_add_f32_e32 v2, v2, v27
	v_cvt_pk_bf16_f32 v28, v13, v69
	v_readlane_b32 vcc_hi, v155, 21
	v_lshlrev_b32_e32 v28, 16, v28
	v_mul_f32_e32 v29, vcc_hi, v184
	v_add_f32_e32 v3, v3, v28
	v_add_f32_e32 v2, v2, v29
	v_cvt_pk_bf16_f32 v26, v14, v69
	v_readlane_b32 vcc_lo, v155, 22
	v_lshlrev_b32_e32 v26, 16, v26
	v_mul_f32_e32 v27, vcc_lo, v185
	v_add_f32_e32 v3, v3, v26
	v_add_f32_e32 v2, v2, v27
	v_cvt_pk_bf16_f32 v28, v15, v69
	v_readlane_b32 vcc_hi, v155, 23
	v_lshlrev_b32_e32 v28, 16, v28
	v_mul_f32_e32 v29, vcc_hi, v186
	v_add_f32_e32 v3, v3, v28
	v_add_f32_e32 v2, v2, v29
	v_add_u32_e32 v24, 0x2080, v4
	v_add_u32_e32 v25, 0x2480, v4
	ds_read2_b32 v[8:9], v24 offset1:65
	ds_read2_b32 v[10:11], v24 offset0:130 offset1:195
	ds_read2_b32 v[12:13], v25 offset0:4 offset1:69
	ds_read2_b32 v[14:15], v25 offset0:134 offset1:199
	s_waitcnt lgkmcnt(4)
	v_cvt_pk_bf16_f32 v26, v16, v69
	v_readlane_b32 vcc_lo, v155, 24
	v_lshlrev_b32_e32 v26, 16, v26
	v_mul_f32_e32 v27, vcc_lo, v187
	v_add_f32_e32 v3, v3, v26
	v_add_f32_e32 v2, v2, v27
	v_cvt_pk_bf16_f32 v28, v17, v69
	v_readlane_b32 vcc_hi, v155, 25
	v_lshlrev_b32_e32 v28, 16, v28
	v_mul_f32_e32 v29, vcc_hi, v188
	v_add_f32_e32 v3, v3, v28
	v_add_f32_e32 v2, v2, v29
	v_cvt_pk_bf16_f32 v26, v18, v69
	v_readlane_b32 vcc_lo, v155, 26
	v_lshlrev_b32_e32 v26, 16, v26
	v_mul_f32_e32 v27, vcc_lo, v189
	v_add_f32_e32 v3, v3, v26
	v_add_f32_e32 v2, v2, v27
	v_cvt_pk_bf16_f32 v28, v19, v69
	v_readlane_b32 vcc_hi, v155, 27
	v_lshlrev_b32_e32 v28, 16, v28
	v_mul_f32_e32 v29, vcc_hi, v190
	v_add_f32_e32 v3, v3, v28
	v_add_f32_e32 v2, v2, v29
	v_cvt_pk_bf16_f32 v26, v20, v69
	v_readlane_b32 vcc_lo, v155, 28
	v_lshlrev_b32_e32 v26, 16, v26
	v_mul_f32_e32 v27, vcc_lo, v191
	v_add_f32_e32 v3, v3, v26
	v_add_f32_e32 v2, v2, v27
	v_cvt_pk_bf16_f32 v28, v21, v69
	v_readlane_b32 vcc_hi, v155, 29
	v_lshlrev_b32_e32 v28, 16, v28
	v_mul_f32_e32 v29, vcc_hi, v192
	v_add_f32_e32 v3, v3, v28
	v_add_f32_e32 v2, v2, v29
	v_cvt_pk_bf16_f32 v26, v22, v69
	v_readlane_b32 vcc_lo, v155, 30
	v_lshlrev_b32_e32 v26, 16, v26
	v_mul_f32_e32 v27, vcc_lo, v193
	v_add_f32_e32 v3, v3, v26
	v_add_f32_e32 v2, v2, v27
	v_cvt_pk_bf16_f32 v28, v23, v69
	v_readlane_b32 vcc_hi, v155, 31
	v_lshlrev_b32_e32 v28, 16, v28
	v_mul_f32_e32 v29, vcc_hi, v194
	v_add_f32_e32 v3, v3, v28
	v_add_f32_e32 v2, v2, v29
	v_add_u32_e32 v24, 0x28a0, v4
	v_add_u32_e32 v25, 0x2ca0, v4
	ds_read2_b32 v[16:17], v24 offset1:65
	ds_read2_b32 v[18:19], v24 offset0:130 offset1:195
	ds_read2_b32 v[20:21], v25 offset0:4 offset1:69
	ds_read2_b32 v[22:23], v25 offset0:134 offset1:199
	s_waitcnt vmcnt(16)
	s_waitcnt lgkmcnt(4)
	v_cvt_pk_bf16_f32 v26, v8, v69
	v_readlane_b32 vcc_lo, v155, 32
	v_lshlrev_b32_e32 v26, 16, v26
	v_mul_f32_e32 v27, vcc_lo, v195
	v_add_f32_e32 v3, v3, v26
	v_add_f32_e32 v2, v2, v27
	v_cvt_pk_bf16_f32 v28, v9, v69
	v_readlane_b32 vcc_hi, v155, 33
	v_lshlrev_b32_e32 v28, 16, v28
	v_mul_f32_e32 v29, vcc_hi, v196
	v_add_f32_e32 v3, v3, v28
	v_add_f32_e32 v2, v2, v29
	v_cvt_pk_bf16_f32 v26, v10, v69
	v_readlane_b32 vcc_lo, v155, 34
	v_lshlrev_b32_e32 v26, 16, v26
	v_mul_f32_e32 v27, vcc_lo, v197
	v_add_f32_e32 v3, v3, v26
	v_add_f32_e32 v2, v2, v27
	v_cvt_pk_bf16_f32 v28, v11, v69
	v_readlane_b32 vcc_hi, v155, 35
	v_lshlrev_b32_e32 v28, 16, v28
	v_mul_f32_e32 v29, vcc_hi, v198
	v_add_f32_e32 v3, v3, v28
	v_add_f32_e32 v2, v2, v29
	v_cvt_pk_bf16_f32 v26, v12, v69
	v_readlane_b32 vcc_lo, v155, 36
	v_lshlrev_b32_e32 v26, 16, v26
	v_mul_f32_e32 v27, vcc_lo, v199
	v_add_f32_e32 v3, v3, v26
	v_add_f32_e32 v2, v2, v27
	v_cvt_pk_bf16_f32 v28, v13, v69
	v_readlane_b32 vcc_hi, v155, 37
	v_lshlrev_b32_e32 v28, 16, v28
	v_mul_f32_e32 v29, vcc_hi, v200
	v_add_f32_e32 v3, v3, v28
	v_add_f32_e32 v2, v2, v29
	v_cvt_pk_bf16_f32 v26, v14, v69
	v_readlane_b32 vcc_lo, v155, 38
	v_lshlrev_b32_e32 v26, 16, v26
	v_mul_f32_e32 v27, vcc_lo, v201
	v_add_f32_e32 v3, v3, v26
	v_add_f32_e32 v2, v2, v27
	v_cvt_pk_bf16_f32 v28, v15, v69
	v_readlane_b32 vcc_hi, v155, 39
	v_lshlrev_b32_e32 v28, 16, v28
	v_mul_f32_e32 v29, vcc_hi, v202
	v_add_f32_e32 v3, v3, v28
	v_add_f32_e32 v2, v2, v29
	v_add_u32_e32 v24, 0x30c0, v4
	v_add_u32_e32 v25, 0x34c0, v4
	ds_read2_b32 v[8:9], v24 offset1:65
	ds_read2_b32 v[10:11], v24 offset0:130 offset1:195
	ds_read2_b32 v[12:13], v25 offset0:4 offset1:69
	ds_read2_b32 v[14:15], v25 offset0:134 offset1:199
	s_waitcnt lgkmcnt(4)
; __device__ __forceinline__ unsigned f2bf(float f) { return pk2(f, 0.f) & 0xffffu; }
; __device__ __forceinline__ void p0_transpose_item(const float* W, int K, int N, bf16* WT, float* scr, int item, int lane, const float* scale, const float* cb, float* c1, float* c2) {
;     ...
;     if (c1) { float a1 = 0.f, a2 = 0.f;
;         for (int kk = 0; kk < 64; ++kk) { a1 += __uint_as_float(f2bf(scr[kk * 65 + lane]) << 16); a2 += cb[k0 + kk] * W[(size_t)(k0 + kk) * N + n0 + lane]; }
;         atomicAdd(c1 + n0 + lane, a1); atomicAdd(c2 + n0 + lane, a2); }
	v_cvt_pk_bf16_f32 v26, v16, v69
	v_readlane_b32 vcc_lo, v155, 40
	v_lshlrev_b32_e32 v26, 16, v26
	v_mul_f32_e32 v27, vcc_lo, v203
	v_add_f32_e32 v3, v3, v26
	v_add_f32_e32 v2, v2, v27
	v_cvt_pk_bf16_f32 v28, v17, v69
	v_readlane_b32 vcc_hi, v155, 41
	v_lshlrev_b32_e32 v28, 16, v28
	v_mul_f32_e32 v29, vcc_hi, v204
	v_add_f32_e32 v3, v3, v28
	v_add_f32_e32 v2, v2, v29
	v_cvt_pk_bf16_f32 v26, v18, v69
	v_readlane_b32 vcc_lo, v155, 42
	v_lshlrev_b32_e32 v26, 16, v26
	v_mul_f32_e32 v27, vcc_lo, v205
	v_add_f32_e32 v3, v3, v26
	v_add_f32_e32 v2, v2, v27
	v_cvt_pk_bf16_f32 v28, v19, v69
	v_readlane_b32 vcc_hi, v155, 43
	v_lshlrev_b32_e32 v28, 16, v28
	v_mul_f32_e32 v29, vcc_hi, v206
	v_add_f32_e32 v3, v3, v28
	v_add_f32_e32 v2, v2, v29
	v_cvt_pk_bf16_f32 v26, v20, v69
	v_readlane_b32 vcc_lo, v155, 44
	v_lshlrev_b32_e32 v26, 16, v26
	v_mul_f32_e32 v27, vcc_lo, v207
	v_add_f32_e32 v3, v3, v26
	v_add_f32_e32 v2, v2, v27
	v_cvt_pk_bf16_f32 v28, v21, v69
	v_readlane_b32 vcc_hi, v155, 45
	v_lshlrev_b32_e32 v28, 16, v28
	v_mul_f32_e32 v29, vcc_hi, v208
	v_add_f32_e32 v3, v3, v28
	v_add_f32_e32 v2, v2, v29
	v_cvt_pk_bf16_f32 v26, v22, v69
	v_readlane_b32 vcc_lo, v155, 46
	v_lshlrev_b32_e32 v26, 16, v26
	v_mul_f32_e32 v27, vcc_lo, v209
	v_add_f32_e32 v3, v3, v26
	v_add_f32_e32 v2, v2, v27
	v_cvt_pk_bf16_f32 v28, v23, v69
	v_readlane_b32 vcc_hi, v155, 47
	v_lshlrev_b32_e32 v28, 16, v28
	v_mul_f32_e32 v29, vcc_hi, v210
	v_add_f32_e32 v3, v3, v28
	v_add_f32_e32 v2, v2, v29
	v_add_u32_e32 v24, 0x38e0, v4
	v_add_u32_e32 v25, 0x3ce0, v4
	ds_read2_b32 v[16:17], v24 offset1:65
	ds_read2_b32 v[18:19], v24 offset0:130 offset1:195
	ds_read2_b32 v[20:21], v25 offset0:4 offset1:69
	ds_read2_b32 v[22:23], v25 offset0:134 offset1:199
	s_waitcnt vmcnt(0)
	s_waitcnt lgkmcnt(4)
	v_cvt_pk_bf16_f32 v26, v8, v69
	v_readlane_b32 vcc_lo, v155, 48
	v_lshlrev_b32_e32 v26, 16, v26
	v_mul_f32_e32 v27, vcc_lo, v211
	v_add_f32_e32 v3, v3, v26
	v_add_f32_e32 v2, v2, v27
	v_cvt_pk_bf16_f32 v28, v9, v69
	v_readlane_b32 vcc_hi, v155, 49
	v_lshlrev_b32_e32 v28, 16, v28
	v_mul_f32_e32 v29, vcc_hi, v212
	v_add_f32_e32 v3, v3, v28
	v_add_f32_e32 v2, v2, v29
	v_cvt_pk_bf16_f32 v26, v10, v69
	v_readlane_b32 vcc_lo, v155, 50
	v_lshlrev_b32_e32 v26, 16, v26
	v_mul_f32_e32 v27, vcc_lo, v213
	v_add_f32_e32 v3, v3, v26
	v_add_f32_e32 v2, v2, v27
	v_cvt_pk_bf16_f32 v28, v11, v69
	v_readlane_b32 vcc_hi, v155, 51
	v_lshlrev_b32_e32 v28, 16, v28
	v_mul_f32_e32 v29, vcc_hi, v224
	v_add_f32_e32 v3, v3, v28
	v_add_f32_e32 v2, v2, v29
	v_cvt_pk_bf16_f32 v26, v12, v69
	v_readlane_b32 vcc_lo, v155, 52
	v_lshlrev_b32_e32 v26, 16, v26
	v_mul_f32_e32 v27, vcc_lo, v225
	v_add_f32_e32 v3, v3, v26
	v_add_f32_e32 v2, v2, v27
	v_cvt_pk_bf16_f32 v28, v13, v69
	v_readlane_b32 vcc_hi, v155, 53
	v_lshlrev_b32_e32 v28, 16, v28
	v_mul_f32_e32 v29, vcc_hi, v226
	v_add_f32_e32 v3, v3, v28
	v_add_f32_e32 v2, v2, v29
	v_cvt_pk_bf16_f32 v26, v14, v69
	v_readlane_b32 vcc_lo, v155, 54
	v_lshlrev_b32_e32 v26, 16, v26
	v_mul_f32_e32 v27, vcc_lo, v227
	v_add_f32_e32 v3, v3, v26
	v_add_f32_e32 v2, v2, v27
	v_cvt_pk_bf16_f32 v28, v15, v69
	v_readlane_b32 vcc_hi, v155, 55
	v_lshlrev_b32_e32 v28, 16, v28
	v_mul_f32_e32 v29, vcc_hi, v228
	v_add_f32_e32 v3, v3, v28
	v_add_f32_e32 v2, v2, v29
	s_waitcnt lgkmcnt(0)
	v_cvt_pk_bf16_f32 v26, v16, v69
	v_readlane_b32 vcc_lo, v155, 56
	v_lshlrev_b32_e32 v26, 16, v26
	v_mul_f32_e32 v27, vcc_lo, v229
	v_add_f32_e32 v3, v3, v26
	v_add_f32_e32 v2, v2, v27
	v_cvt_pk_bf16_f32 v28, v17, v69
	v_readlane_b32 vcc_hi, v155, 57
	v_lshlrev_b32_e32 v28, 16, v28
	v_mul_f32_e32 v29, vcc_hi, v230
	v_add_f32_e32 v3, v3, v28
	v_add_f32_e32 v2, v2, v29
	v_cvt_pk_bf16_f32 v26, v18, v69
	v_readlane_b32 vcc_lo, v155, 58
	v_lshlrev_b32_e32 v26, 16, v26
	v_mul_f32_e32 v27, vcc_lo, v231
	v_add_f32_e32 v3, v3, v26
	v_add_f32_e32 v2, v2, v27
	v_cvt_pk_bf16_f32 v28, v19, v69
	v_readlane_b32 vcc_hi, v155, 59
	v_lshlrev_b32_e32 v28, 16, v28
	v_mul_f32_e32 v29, vcc_hi, v232
	v_add_f32_e32 v3, v3, v28
	v_add_f32_e32 v2, v2, v29
	v_cvt_pk_bf16_f32 v26, v20, v69
	v_readlane_b32 vcc_lo, v155, 60
	v_lshlrev_b32_e32 v26, 16, v26
	v_mul_f32_e32 v27, vcc_lo, v233
	v_add_f32_e32 v3, v3, v26
	v_add_f32_e32 v2, v2, v27
	v_cvt_pk_bf16_f32 v28, v21, v69
	v_readlane_b32 vcc_hi, v155, 61
	v_lshlrev_b32_e32 v28, 16, v28
	v_mul_f32_e32 v29, vcc_hi, v234
	v_add_f32_e32 v3, v3, v28
	v_add_f32_e32 v2, v2, v29
	v_cvt_pk_bf16_f32 v26, v22, v69
	v_readlane_b32 vcc_lo, v155, 62
	v_lshlrev_b32_e32 v26, 16, v26
	v_mul_f32_e32 v27, vcc_lo, v235
	v_add_f32_e32 v3, v3, v26
	v_add_f32_e32 v2, v2, v27
	v_cvt_pk_bf16_f32 v28, v23, v69
	v_readlane_b32 vcc_hi, v155, 63
	v_lshlrev_b32_e32 v28, 16, v28
	v_mul_f32_e32 v29, vcc_hi, v236
	v_add_f32_e32 v3, v3, v28
	v_add_f32_e32 v2, v2, v29
	s_add_u32 s4, s37, s8
	s_addc_u32 s5, s38, s9
	s_add_u32 s7, s39, s8
	s_addc_u32 s8, s40, s9
	s_add_u32 s4, s4, s62
	s_addc_u32 s5, s5, 0
	v_mov_b32_e32 v73, v69
	v_lshl_add_u64 v[0:1], s[4:5], 0, v[72:73]
	s_add_u32 s4, s7, s62
	s_addc_u32 s5, s8, 0
	global_atomic_add_f32 v[0:1], v3, off
	v_lshl_add_u64 v[0:1], s[4:5], 0, v[72:73]
	global_atomic_add_f32 v[0:1], v2, off
	s_waitcnt lgkmcnt(0)

; __device__ __forceinline__ void p0_transpose_item(const float* W, int K, int N, bf16* WT, float* scr, int item, int lane, const float* scale, const float* cb, float* c1, float* c2) {
;     const int nblk = N / 64, kb = item / nblk, nb = item % nblk, k0 = 64 * kb, n0 = 64 * nb;
;     const int lr = lane >> 4, lc = (lane & 15) * 4;
;     f32x4 v[16];
; #pragma unroll
;     for (int i = 0; i < 16; ++i) v[i] = *(const f32x4*)(W + (size_t)(k0 + 4 * i + lr) * N + n0 + lc);
; #pragma unroll
;     for (int i = 0; i < 16; ++i) { const int kk = 4 * i + lr; f32x4 w = v[i]; if (scale) w = w * scale[k0 + kk]; float* d = scr + kk * 65 + lc; d[0] = w[0]; d[1] = w[1]; d[2] = w[2]; d[3] = w[3]; }
.LBB0_1415:
	s_andn2_b64 vcc, exec, s[2:3]
	s_cbranch_vccnz .LBB0_1443
	s_lshl_b64 s[6:7], s[0:1], 24
	s_add_u32 s4, s16, s6
	s_addc_u32 s5, s17, s7
	s_lshl_b32 s2, s0, 11
	s_ashr_i32 s3, s2, 31
	v_readlane_b32 s48, v253, 18
	s_lshl_b64 s[2:3], s[2:3], 2
	v_readlane_b32 s58, v253, 28
	v_readlane_b32 s59, v253, 29
	s_add_u32 s8, s58, s2
	s_addc_u32 s9, s59, s3
	s_lshl_b32 s46, s44, 1
	s_lshl_b32 s14, s44, 6
	s_add_i32 s46, s46, 0x1da00
	s_and_b32 s48, s14, 0x7c0
	s_and_b32 s47, s46, 0x1ffc0
	s_lshl_b32 s45, s48, 2
	s_add_u32 s4, s4, s45
	v_or_b32_e32 v64, s47, v69
	s_addc_u32 s5, s5, 0
	v_lshlrev_b32_e32 v168, 2, v68
	v_lshl_add_u64 v[0:1], s[4:5], 0, v[168:169]
	v_lshlrev_b32_e32 v168, 13, v64
	v_lshl_add_u64 v[0:1], v[0:1], 0, v[168:169]
	v_add_co_u32_e32 v2, vcc, s90, v0
	s_mov_b32 s4, 0x20000
	s_nop 0
	v_addc_co_u32_e32 v3, vcc, 0, v1, vcc
	global_load_dwordx4 v[56:59], v[0:1], off
	global_load_dwordx4 v[60:63], v[2:3], off
	v_add_co_u32_e32 v2, vcc, s88, v0
	v_readlane_b32 s14, v254, 34
	s_nop 0
	v_addc_co_u32_e32 v3, vcc, 0, v1, vcc
	v_add_co_u32_e32 v4, vcc, s85, v0
	v_readlane_b32 s15, v254, 35
	s_nop 0
	v_addc_co_u32_e32 v5, vcc, 0, v1, vcc
	global_load_dwordx4 v[48:51], v[2:3], off
	global_load_dwordx4 v[52:55], v[4:5], off
	v_add_co_u32_e32 v2, vcc, s4, v0
	s_mov_b32 s4, 0x28000
	s_nop 0
	v_addc_co_u32_e32 v3, vcc, 0, v1, vcc
	v_add_co_u32_e32 v4, vcc, s4, v0
	s_mov_b32 s4, 0x30000
	s_nop 0
	v_addc_co_u32_e32 v5, vcc, 0, v1, vcc
	global_load_dwordx4 v[40:43], v[2:3], off
	global_load_dwordx4 v[44:47], v[4:5], off
	v_add_co_u32_e32 v2, vcc, s4, v0
	s_mov_b32 s4, 0x38000
	s_nop 0
	v_addc_co_u32_e32 v3, vcc, 0, v1, vcc
	v_add_co_u32_e32 v4, vcc, s4, v0
	s_mov_b32 s4, 0x40000
	s_nop 0
	v_addc_co_u32_e32 v5, vcc, 0, v1, vcc
	global_load_dwordx4 v[32:35], v[2:3], off
	global_load_dwordx4 v[36:39], v[4:5], off
	v_add_co_u32_e32 v2, vcc, s4, v0
	s_mov_b32 s4, 0x48000
	s_nop 0
	v_addc_co_u32_e32 v3, vcc, 0, v1, vcc
	v_add_co_u32_e32 v4, vcc, s4, v0
	s_mov_b32 s4, 0x50000
	s_nop 0
	v_addc_co_u32_e32 v5, vcc, 0, v1, vcc
	global_load_dwordx4 v[24:27], v[2:3], off
	global_load_dwordx4 v[28:31], v[4:5], off
	v_add_co_u32_e32 v2, vcc, s4, v0
	s_mov_b32 s4, 0x58000
	s_nop 0
	v_addc_co_u32_e32 v3, vcc, 0, v1, vcc
	v_add_co_u32_e32 v4, vcc, s4, v0
	s_mov_b32 s4, 0x60000
	s_nop 0
	v_addc_co_u32_e32 v5, vcc, 0, v1, vcc
	global_load_dwordx4 v[16:19], v[2:3], off
	global_load_dwordx4 v[20:23], v[4:5], off
	v_add_co_u32_e32 v2, vcc, s4, v0
	v_cndmask_b32_e64 v65, 0, 1, s[14:15]
	s_nop 0
	v_addc_co_u32_e32 v3, vcc, 0, v1, vcc
	v_add_co_u32_e32 v4, vcc, 0x68000, v0
	v_cmp_ne_u32_e64 s[4:5], 1, v65
	s_nop 0
	v_addc_co_u32_e32 v5, vcc, 0, v1, vcc
	global_load_dwordx4 v[8:11], v[2:3], off
	global_load_dwordx4 v[12:15], v[4:5], off
	v_add_co_u32_e32 v2, vcc, 0x70000, v0
	v_add_lshl_u32 v75, s47, v69, 2
	s_nop 0
	v_addc_co_u32_e32 v3, vcc, 0, v1, vcc
	v_add_co_u32_e32 v4, vcc, 0x78000, v0
	v_readlane_b32 s49, v253, 19
	s_nop 0
	v_addc_co_u32_e32 v5, vcc, 0, v1, vcc
	global_load_dwordx4 v[0:3], v[2:3], off
	s_nop 0
	global_load_dwordx4 v[4:7], v[4:5], off
	s_andn2_b64 vcc, exec, s[14:15]
	v_readlane_b32 s50, v253, 20
	v_readlane_b32 s51, v253, 21
	v_readlane_b32 s52, v253, 22
	v_readlane_b32 s53, v253, 23
	v_readlane_b32 s54, v253, 24
	v_readlane_b32 s55, v253, 25
	v_readlane_b32 s56, v253, 26
	v_readlane_b32 s57, v253, 27
	v_readlane_b32 s60, v253, 30
	v_readlane_b32 s61, v253, 31
	v_readlane_b32 s62, v253, 32
	v_readlane_b32 s63, v253, 33
	s_cbranch_vccnz .LBB0_1449
	v_lshlrev_b32_e32 v64, 2, v64
	global_load_dword v64, v64, s[8:9]
	s_nop 0
	global_load_dword v92, v75, s[8:9] offset:16
	global_load_dword v126, v75, s[8:9] offset:32
	global_load_dword v128, v75, s[8:9] offset:48
	global_load_dword v130, v75, s[8:9] offset:64
	global_load_dword v132, v75, s[8:9] offset:80
	global_load_dword v134, v75, s[8:9] offset:96
	global_load_dword v136, v75, s[8:9] offset:112
	global_load_dword v138, v75, s[8:9] offset:128
	global_load_dword v140, v75, s[8:9] offset:144
	global_load_dword v142, v75, s[8:9] offset:160
	global_load_dword v144, v75, s[8:9] offset:176
	global_load_dword v146, v75, s[8:9] offset:192
	global_load_dword v148, v75, s[8:9] offset:208
	global_load_dword v150, v75, s[8:9] offset:224
	global_load_dword v152, v75, s[8:9] offset:240
	s_waitcnt vmcnt(0)
	v_pk_mul_f32 v[76:77], v[58:59], v[64:65] op_sel_hi:[1,0]
	v_pk_mul_f32 v[78:79], v[56:57], v[64:65] op_sel_hi:[1,0]
	v_pk_mul_f32 v[66:67], v[62:63], v[92:93] op_sel_hi:[1,0]
	v_pk_mul_f32 v[64:65], v[60:61], v[92:93] op_sel_hi:[1,0]
	s_cbranch_execnz .LBB0_1419

; __device__ __forceinline__ void p0_transpose_item(const float* W, int K, int N, bf16* WT, float* scr, int item, int lane, const float* scale, const float* cb, float* c1, float* c2) {
;     ...
;     for (int i = 0; i < 16; ++i) { const int kk = 4 * i + lr; f32x4 w = v[i]; if (scale) w = w * scale[k0 + kk]; float* d = scr + kk * 65 + lc; d[0] = w[0]; d[1] = w[1]; d[2] = w[2]; d[3] = w[3]; }
.LBB0_1419:
	s_and_b64 vcc, exec, s[4:5]
	ds_write2_b32 v71, v78, v79 offset1:1
	ds_write2_b32 v71, v76, v77 offset0:2 offset1:3
	ds_write2_b32 v90, v64, v65 offset1:1
	ds_write2_b32 v90, v66, v67 offset0:2 offset1:3
	s_cbranch_vccnz .LBB0_1450
	v_pk_mul_f32 v[60:61], v[50:51], v[126:127] op_sel_hi:[1,0]
	v_pk_mul_f32 v[62:63], v[48:49], v[126:127] op_sel_hi:[1,0]
	v_pk_mul_f32 v[58:59], v[54:55], v[128:129] op_sel_hi:[1,0]
	v_pk_mul_f32 v[56:57], v[52:53], v[128:129] op_sel_hi:[1,0]
	s_cbranch_execnz .LBB0_1422

; __device__ __forceinline__ void p0_transpose_item(const float* W, int K, int N, bf16* WT, float* scr, int item, int lane, const float* scale, const float* cb, float* c1, float* c2) {
;     ...
;     for (int i = 0; i < 16; ++i) { const int kk = 4 * i + lr; f32x4 w = v[i]; if (scale) w = w * scale[k0 + kk]; float* d = scr + kk * 65 + lc; d[0] = w[0]; d[1] = w[1]; d[2] = w[2]; d[3] = w[3]; }
.LBB0_1422:
	s_waitcnt vmcnt(0)
	v_add_u32_e32 v48, 0x410, v90
	ds_write2_b32 v48, v62, v63 offset1:1
	v_add_u32_e32 v48, 0x418, v90
	ds_write2_b32 v48, v60, v61 offset1:1
	v_add_u32_e32 v48, 0x820, v90
	ds_write2_b32 v48, v56, v57 offset1:1
	v_add_u32_e32 v48, 0x828, v90
	s_and_b64 vcc, exec, s[4:5]
	ds_write2_b32 v48, v58, v59 offset1:1
	s_cbranch_vccnz .LBB0_1451
	v_pk_mul_f32 v[52:53], v[42:43], v[130:131] op_sel_hi:[1,0]
	v_pk_mul_f32 v[54:55], v[40:41], v[130:131] op_sel_hi:[1,0]
	v_pk_mul_f32 v[50:51], v[46:47], v[132:133] op_sel_hi:[1,0]
	v_pk_mul_f32 v[48:49], v[44:45], v[132:133] op_sel_hi:[1,0]
	s_cbranch_execnz .LBB0_1425

; __device__ __forceinline__ void p0_transpose_item(const float* W, int K, int N, bf16* WT, float* scr, int item, int lane, const float* scale, const float* cb, float* c1, float* c2) {
;     ...
;     for (int i = 0; i < 16; ++i) { const int kk = 4 * i + lr; f32x4 w = v[i]; if (scale) w = w * scale[k0 + kk]; float* d = scr + kk * 65 + lc; d[0] = w[0]; d[1] = w[1]; d[2] = w[2]; d[3] = w[3]; }
.LBB0_1425:
	v_add_u32_e32 v40, 0xc30, v90
	ds_write2_b32 v40, v54, v55 offset1:1
	v_add_u32_e32 v40, 0xc38, v90
	ds_write2_b32 v40, v52, v53 offset1:1
	v_add_u32_e32 v40, 0x1040, v90
	ds_write2_b32 v40, v48, v49 offset1:1
	v_add_u32_e32 v40, 0x1048, v90
	s_and_b64 vcc, exec, s[4:5]
	ds_write2_b32 v40, v50, v51 offset1:1
	s_cbranch_vccnz .LBB0_1452
	v_pk_mul_f32 v[44:45], v[34:35], v[134:135] op_sel_hi:[1,0]
	v_pk_mul_f32 v[46:47], v[32:33], v[134:135] op_sel_hi:[1,0]
	v_pk_mul_f32 v[42:43], v[38:39], v[136:137] op_sel_hi:[1,0]
	v_pk_mul_f32 v[40:41], v[36:37], v[136:137] op_sel_hi:[1,0]
	s_cbranch_execnz .LBB0_1428

; __device__ __forceinline__ void p0_transpose_item(const float* W, int K, int N, bf16* WT, float* scr, int item, int lane, const float* scale, const float* cb, float* c1, float* c2) {
;     ...
;     for (int i = 0; i < 16; ++i) { const int kk = 4 * i + lr; f32x4 w = v[i]; if (scale) w = w * scale[k0 + kk]; float* d = scr + kk * 65 + lc; d[0] = w[0]; d[1] = w[1]; d[2] = w[2]; d[3] = w[3]; }
.LBB0_1428:
	v_add_u32_e32 v32, 0x1450, v90
	ds_write2_b32 v32, v46, v47 offset1:1
	v_add_u32_e32 v32, 0x1458, v90
	ds_write2_b32 v32, v44, v45 offset1:1
	v_add_u32_e32 v32, 0x1860, v90
	ds_write2_b32 v32, v40, v41 offset1:1
	v_add_u32_e32 v32, 0x1868, v90
	s_and_b64 vcc, exec, s[4:5]
	ds_write2_b32 v32, v42, v43 offset1:1
	s_cbranch_vccnz .LBB0_1453
	v_pk_mul_f32 v[36:37], v[26:27], v[138:139] op_sel_hi:[1,0]
	v_pk_mul_f32 v[38:39], v[24:25], v[138:139] op_sel_hi:[1,0]
	v_pk_mul_f32 v[34:35], v[30:31], v[140:141] op_sel_hi:[1,0]
	v_pk_mul_f32 v[32:33], v[28:29], v[140:141] op_sel_hi:[1,0]
	s_cbranch_execnz .LBB0_1431

; __device__ __forceinline__ void p0_transpose_item(const float* W, int K, int N, bf16* WT, float* scr, int item, int lane, const float* scale, const float* cb, float* c1, float* c2) {
;     ...
;     for (int i = 0; i < 16; ++i) { const int kk = 4 * i + lr; f32x4 w = v[i]; if (scale) w = w * scale[k0 + kk]; float* d = scr + kk * 65 + lc; d[0] = w[0]; d[1] = w[1]; d[2] = w[2]; d[3] = w[3]; }
.LBB0_1431:
	v_add_u32_e32 v24, 0x1c70, v90
	ds_write2_b32 v24, v38, v39 offset1:1
	v_add_u32_e32 v24, 0x1c78, v90
	ds_write2_b32 v24, v36, v37 offset1:1
	v_add_u32_e32 v24, 0x2080, v90
	ds_write2_b32 v24, v32, v33 offset1:1
	v_add_u32_e32 v24, 0x2088, v90
	s_and_b64 vcc, exec, s[4:5]
	ds_write2_b32 v24, v34, v35 offset1:1
	s_cbranch_vccnz .LBB0_1454
	v_pk_mul_f32 v[28:29], v[18:19], v[142:143] op_sel_hi:[1,0]
	v_pk_mul_f32 v[30:31], v[16:17], v[142:143] op_sel_hi:[1,0]
	v_pk_mul_f32 v[26:27], v[22:23], v[144:145] op_sel_hi:[1,0]
	v_pk_mul_f32 v[24:25], v[20:21], v[144:145] op_sel_hi:[1,0]
	s_cbranch_execnz .LBB0_1434

; __device__ __forceinline__ void p0_transpose_item(const float* W, int K, int N, bf16* WT, float* scr, int item, int lane, const float* scale, const float* cb, float* c1, float* c2) {
;     ...
;     for (int i = 0; i < 16; ++i) { const int kk = 4 * i + lr; f32x4 w = v[i]; if (scale) w = w * scale[k0 + kk]; float* d = scr + kk * 65 + lc; d[0] = w[0]; d[1] = w[1]; d[2] = w[2]; d[3] = w[3]; }
.LBB0_1434:
	v_add_u32_e32 v16, 0x2490, v90
	ds_write2_b32 v16, v30, v31 offset1:1
	v_add_u32_e32 v16, 0x2498, v90
	ds_write2_b32 v16, v28, v29 offset1:1
	v_add_u32_e32 v16, 0x28a0, v90
	ds_write2_b32 v16, v24, v25 offset1:1
	v_add_u32_e32 v16, 0x28a8, v90
	s_and_b64 vcc, exec, s[4:5]
	ds_write2_b32 v16, v26, v27 offset1:1
	s_cbranch_vccnz .LBB0_1455
	v_pk_mul_f32 v[20:21], v[10:11], v[146:147] op_sel_hi:[1,0]
	v_pk_mul_f32 v[22:23], v[8:9], v[146:147] op_sel_hi:[1,0]
	v_pk_mul_f32 v[18:19], v[14:15], v[148:149] op_sel_hi:[1,0]
	v_pk_mul_f32 v[16:17], v[12:13], v[148:149] op_sel_hi:[1,0]
	s_cbranch_execnz .LBB0_1437

; __device__ __forceinline__ void p0_transpose_item(const float* W, int K, int N, bf16* WT, float* scr, int item, int lane, const float* scale, const float* cb, float* c1, float* c2) {
;     ...
;     for (int i = 0; i < 16; ++i) { const int kk = 4 * i + lr; f32x4 w = v[i]; if (scale) w = w * scale[k0 + kk]; float* d = scr + kk * 65 + lc; d[0] = w[0]; d[1] = w[1]; d[2] = w[2]; d[3] = w[3]; }
.LBB0_1437:
	v_add_u32_e32 v8, 0x2cb0, v90
	ds_write2_b32 v8, v22, v23 offset1:1
	v_add_u32_e32 v8, 0x2cb8, v90
	ds_write2_b32 v8, v20, v21 offset1:1
	v_add_u32_e32 v8, 0x30c0, v90
	ds_write2_b32 v8, v16, v17 offset1:1
	v_add_u32_e32 v8, 0x30c8, v90
	s_and_b64 vcc, exec, s[4:5]
	ds_write2_b32 v8, v18, v19 offset1:1
	s_cbranch_vccnz .LBB0_1456
	v_pk_mul_f32 v[12:13], v[2:3], v[150:151] op_sel_hi:[1,0]
	v_pk_mul_f32 v[14:15], v[0:1], v[150:151] op_sel_hi:[1,0]
	v_pk_mul_f32 v[10:11], v[6:7], v[152:153] op_sel_hi:[1,0]
	v_pk_mul_f32 v[8:9], v[4:5], v[152:153] op_sel_hi:[1,0]
	s_cbranch_execnz .LBB0_1440

; #define LDS_WAIT() asm volatile("s_waitcnt lgkmcnt(0)" ::: "memory")
; __device__ __forceinline__ unsigned pk2(float lo, float hi) { unsigned r; asm("v_cvt_pk_bf16_f32 %0, %1, %2" : "=v"(r) : "v"(lo), "v"(hi)); return r; }
; __device__ __forceinline__ void p0_transpose_item(const float* W, int K, int N, bf16* WT, float* scr, int item, int lane, const float* scale, const float* cb, float* c1, float* c2) {
;     ...
;     for (int i = 0; i < 16; ++i) { const int kk = 4 * i + lr; f32x4 w = v[i]; if (scale) w = w * scale[k0 + kk]; float* d = scr + kk * 65 + lc; d[0] = w[0]; d[1] = w[1]; d[2] = w[2]; d[3] = w[3]; }
;     LDS_WAIT(); asm volatile("" ::: "memory");
;     const int c = lane & 7;
; #pragma unroll
;     for (int j = 0; j < 8; ++j) { const int n = (lane >> 3) + 8 * j; const float* sp = scr + (8 * c) * 65 + n;
;         v4u o; o.x = pk2(sp[0 * 65], sp[1 * 65]); o.y = pk2(sp[2 * 65], sp[3 * 65]); o.z = pk2(sp[4 * 65], sp[5 * 65]); o.w = pk2(sp[6 * 65], sp[7 * 65]);
;         *(v4u*)(WT + (size_t)(n0 + n) * K + k0 + 8 * c) = o; }
.LBB0_1440:
	v_add_u32_e32 v0, 0x34d0, v90
	ds_write2_b32 v0, v14, v15 offset1:1
	v_add_u32_e32 v0, 0x34d8, v90
	ds_write2_b32 v0, v12, v13 offset1:1
	v_add_u32_e32 v0, 0x38e0, v90
	ds_write2_b32 v0, v8, v9 offset1:1
	v_add_u32_e32 v0, 0x38e8, v90
	ds_write2_b32 v0, v10, v11 offset1:1
	s_waitcnt lgkmcnt(0)
	ds_read_b32 v2, v81
	ds_read_b32 v3, v81 offset:260
	s_lshl_b64 s[4:5], s[0:1], 22
	s_waitcnt lgkmcnt(0)
	v_cvt_pk_bf16_f32 v2, v2, v3
	ds_read_b32 v3, v81 offset:520
	ds_read_b32 v4, v81 offset:780
	s_waitcnt lgkmcnt(0)
	v_cvt_pk_bf16_f32 v3, v3, v4
	ds_read_b32 v4, v81 offset:1040
	ds_read_b32 v5, v81 offset:1300
	s_waitcnt lgkmcnt(0)
	v_cvt_pk_bf16_f32 v4, v4, v5
	ds_read_b32 v5, v81 offset:1560
	ds_read_b32 v6, v81 offset:1820
	s_lshl_b64 s[4:5], s[4:5], 1
	s_add_u32 s1, s36, s4
	s_addc_u32 s5, s37, s5
	s_lshl_b32 s4, s47, 1
	s_add_u32 s4, s1, s4
	s_addc_u32 s5, s5, 0
	v_lshlrev_b32_e32 v168, 1, v70
	s_waitcnt lgkmcnt(0)
	v_cvt_pk_bf16_f32 v5, v5, v6
	v_or_b32_e32 v6, s48, v80
	v_lshl_add_u64 v[0:1], s[4:5], 0, v[168:169]
	v_lshlrev_b32_e32 v168, 12, v6
	v_lshl_add_u64 v[6:7], v[0:1], 0, v[168:169]
	global_store_dwordx4 v[6:7], v[2:5], off
	ds_read_b32 v2, v81 offset:32
	ds_read_b32 v3, v81 offset:292
	s_waitcnt lgkmcnt(0)
	v_cvt_pk_bf16_f32 v2, v2, v3
	ds_read_b32 v3, v81 offset:552
	ds_read_b32 v4, v81 offset:812
	s_waitcnt lgkmcnt(0)
	v_cvt_pk_bf16_f32 v3, v3, v4
	ds_read_b32 v4, v81 offset:1072
	ds_read_b32 v5, v81 offset:1332
	s_waitcnt lgkmcnt(0)
	v_cvt_pk_bf16_f32 v4, v4, v5
	ds_read_b32 v5, v81 offset:1592
	ds_read_b32 v6, v81 offset:1852
	s_waitcnt lgkmcnt(0)
	v_cvt_pk_bf16_f32 v5, v5, v6
	v_or_b32_e32 v6, s48, v82
	v_lshlrev_b32_e32 v168, 12, v6
	v_lshl_add_u64 v[6:7], v[0:1], 0, v[168:169]
	global_store_dwordx4 v[6:7], v[2:5], off
	ds_read_b32 v2, v81 offset:64
	ds_read_b32 v3, v81 offset:324
	s_waitcnt lgkmcnt(0)
	v_cvt_pk_bf16_f32 v2, v2, v3
	ds_read_b32 v3, v81 offset:584
	ds_read_b32 v4, v81 offset:844
	s_waitcnt lgkmcnt(0)
	v_cvt_pk_bf16_f32 v3, v3, v4
	ds_read_b32 v4, v81 offset:1104
	ds_read_b32 v5, v81 offset:1364
	s_waitcnt lgkmcnt(0)
	v_cvt_pk_bf16_f32 v4, v4, v5
	ds_read_b32 v5, v81 offset:1624
	ds_read_b32 v6, v81 offset:1884
	s_waitcnt lgkmcnt(0)
	v_cvt_pk_bf16_f32 v5, v5, v6
	v_or_b32_e32 v6, s48, v83
	v_lshlrev_b32_e32 v168, 12, v6
	v_lshl_add_u64 v[6:7], v[0:1], 0, v[168:169]
	global_store_dwordx4 v[6:7], v[2:5], off
	ds_read_b32 v2, v81 offset:96
	ds_read_b32 v3, v81 offset:356
	s_waitcnt lgkmcnt(0)
	v_cvt_pk_bf16_f32 v2, v2, v3
	ds_read_b32 v3, v81 offset:616
	ds_read_b32 v4, v81 offset:876
	s_waitcnt lgkmcnt(0)
	v_cvt_pk_bf16_f32 v3, v3, v4
	ds_read_b32 v4, v81 offset:1136
	ds_read_b32 v5, v81 offset:1396
	s_waitcnt lgkmcnt(0)
	v_cvt_pk_bf16_f32 v4, v4, v5
	ds_read_b32 v5, v81 offset:1656
	ds_read_b32 v6, v81 offset:1916
	s_waitcnt lgkmcnt(0)
	v_cvt_pk_bf16_f32 v5, v5, v6
	v_or_b32_e32 v6, s48, v84
	v_lshlrev_b32_e32 v168, 12, v6
	v_lshl_add_u64 v[6:7], v[0:1], 0, v[168:169]
	global_store_dwordx4 v[6:7], v[2:5], off
	ds_read_b32 v2, v81 offset:128
	ds_read_b32 v3, v81 offset:388
	s_waitcnt lgkmcnt(0)
	v_cvt_pk_bf16_f32 v2, v2, v3
	ds_read_b32 v3, v81 offset:648
	ds_read_b32 v4, v81 offset:908
	s_waitcnt lgkmcnt(0)
	v_cvt_pk_bf16_f32 v3, v3, v4
	ds_read_b32 v4, v81 offset:1168
	ds_read_b32 v5, v81 offset:1428
	s_waitcnt lgkmcnt(0)
	v_cvt_pk_bf16_f32 v4, v4, v5
	ds_read_b32 v5, v81 offset:1688
	ds_read_b32 v6, v81 offset:1948
	s_waitcnt lgkmcnt(0)
	v_cvt_pk_bf16_f32 v5, v5, v6
	v_or_b32_e32 v6, s48, v85
	v_lshlrev_b32_e32 v168, 12, v6
	v_lshl_add_u64 v[6:7], v[0:1], 0, v[168:169]
	global_store_dwordx4 v[6:7], v[2:5], off
	ds_read_b32 v2, v81 offset:160
	ds_read_b32 v3, v81 offset:420
	s_waitcnt lgkmcnt(0)
	v_cvt_pk_bf16_f32 v2, v2, v3
	ds_read_b32 v3, v81 offset:680
	ds_read_b32 v4, v81 offset:940
	s_waitcnt lgkmcnt(0)
	v_cvt_pk_bf16_f32 v3, v3, v4
	ds_read_b32 v4, v81 offset:1200
	ds_read_b32 v5, v81 offset:1460
	s_waitcnt lgkmcnt(0)
	v_cvt_pk_bf16_f32 v4, v4, v5
	ds_read_b32 v5, v81 offset:1720
	ds_read_b32 v6, v81 offset:1980
	s_waitcnt lgkmcnt(0)
	v_cvt_pk_bf16_f32 v5, v5, v6
	v_or_b32_e32 v6, s48, v86
	v_lshlrev_b32_e32 v168, 12, v6
	v_lshl_add_u64 v[6:7], v[0:1], 0, v[168:169]
	global_store_dwordx4 v[6:7], v[2:5], off
	ds_read_b32 v2, v81 offset:192
	ds_read_b32 v3, v81 offset:452
	s_waitcnt lgkmcnt(0)
	v_cvt_pk_bf16_f32 v2, v2, v3
	ds_read_b32 v3, v81 offset:712
	ds_read_b32 v4, v81 offset:972
	s_waitcnt lgkmcnt(0)
	v_cvt_pk_bf16_f32 v3, v3, v4
	ds_read_b32 v4, v81 offset:1232
	ds_read_b32 v5, v81 offset:1492
	s_waitcnt lgkmcnt(0)
	v_cvt_pk_bf16_f32 v4, v4, v5
	ds_read_b32 v5, v81 offset:1752
	ds_read_b32 v6, v81 offset:2012
	s_waitcnt lgkmcnt(0)
	v_cvt_pk_bf16_f32 v5, v5, v6
	v_or_b32_e32 v6, s48, v87
	v_lshlrev_b32_e32 v168, 12, v6
	v_lshl_add_u64 v[6:7], v[0:1], 0, v[168:169]
	global_store_dwordx4 v[6:7], v[2:5], off
	ds_read_b32 v2, v81 offset:224
	ds_read_b32 v3, v81 offset:484
	s_waitcnt lgkmcnt(0)
	v_cvt_pk_bf16_f32 v2, v2, v3
	ds_read_b32 v3, v81 offset:744
	ds_read_b32 v4, v81 offset:1004
	s_waitcnt lgkmcnt(0)
	v_cvt_pk_bf16_f32 v3, v3, v4
	ds_read_b32 v4, v81 offset:1264
	ds_read_b32 v5, v81 offset:1524
	s_waitcnt lgkmcnt(0)
	v_cvt_pk_bf16_f32 v4, v4, v5
	ds_read_b32 v5, v81 offset:1784
	ds_read_b32 v6, v81 offset:2044
	s_lshl_b32 s1, s46, 13
	s_and_b32 s1, s1, 0x3ff80000
	s_add_u32 s1, s6, s1
	s_addc_u32 s5, s7, 0
	s_and_b32 s4, s44, 31
	s_waitcnt lgkmcnt(0)
; __device__ __forceinline__ unsigned pk2(float lo, float hi) { unsigned r; asm("v_cvt_pk_bf16_f32 %0, %1, %2" : "=v"(r) : "v"(lo), "v"(hi)); return r; }
; __device__ __forceinline__ unsigned f2bf(float f) { return pk2(f, 0.f) & 0xffffu; }
; __device__ __forceinline__ void p0_transpose_item(const float* W, int K, int N, bf16* WT, float* scr, int item, int lane, const float* scale, const float* cb, float* c1, float* c2) {
;     ...
;     for (int j = 0; j < 8; ++j) { const int n = (lane >> 3) + 8 * j; const float* sp = scr + (8 * c) * 65 + n;
;         v4u o; o.x = pk2(sp[0 * 65], sp[1 * 65]); o.y = pk2(sp[2 * 65], sp[3 * 65]); o.z = pk2(sp[4 * 65], sp[5 * 65]); o.w = pk2(sp[6 * 65], sp[7 * 65]);
;         *(v4u*)(WT + (size_t)(n0 + n) * K + k0 + 8 * c) = o; }
;     if (c1) { float a1 = 0.f, a2 = 0.f;
;         for (int kk = 0; kk < 64; ++kk) { a1 += __uint_as_float(f2bf(scr[kk * 65 + lane]) << 16); a2 += cb[k0 + kk] * W[(size_t)(k0 + kk) * N + n0 + lane]; }
	v_cvt_pk_bf16_f32 v5, v5, v6
	v_or_b32_e32 v6, s48, v88
	s_lshl_b32 s4, s4, 8
	v_readlane_b32 s48, v253, 18
	v_lshlrev_b32_e32 v168, 12, v6
	s_or_b32 s4, s1, s4
	s_lshl_b32 s1, s47, 2
	v_readlane_b32 s60, v253, 30
	v_lshl_add_u64 v[0:1], v[0:1], 0, v[168:169]
	v_readlane_b32 s61, v253, 31
	s_add_u32 s1, s60, s1
	global_store_dwordx4 v[0:1], v[2:5], off
	v_lshl_add_u64 v[0:1], v[72:73], 0, s[4:5]
	s_addc_u32 s8, s61, 0
	s_lshl_b32 s4, s46, 2
	s_and_b32 s4, s4, 0x7ff00
	s_add_u32 s9, s60, s4
	v_mov_b32_e32 v2, 0
	s_addc_u32 s14, s61, 0
	s_mov_b64 s[4:5], 0
	v_mov_b32_e32 v6, v89
	v_mov_b32_e32 v3, v2
	v_readlane_b32 s49, v253, 19
	v_readlane_b32 s50, v253, 20
	v_readlane_b32 s51, v253, 21
	v_readlane_b32 s52, v253, 22
	v_readlane_b32 s53, v253, 23
	v_readlane_b32 s54, v253, 24
	v_readlane_b32 s55, v253, 25
	v_readlane_b32 s56, v253, 26
	v_readlane_b32 s57, v253, 27
	v_readlane_b32 s58, v253, 28
	v_readlane_b32 s59, v253, 29
	v_readlane_b32 s62, v253, 32
	v_readlane_b32 s63, v253, 33
	s_add_u32 s6, s9, s2
	s_addc_u32 s7, s14, s3
	v_and_b32_e32 v154, 63, v252
	v_lshlrev_b32_e32 v154, 2, v154
	v_mov_b32_e32 v156, v0
	v_mov_b32_e32 v157, v1
	global_load_dword v155, v154, s[6:7]
	s_mov_b64 s[6:7], 0x2000
	global_load_dword v158, v[156:157], off
	v_lshl_add_u64 v[156:157], v[156:157], 0, s[6:7]
	global_load_dword v159, v[156:157], off
	v_lshl_add_u64 v[156:157], v[156:157], 0, s[6:7]
	global_load_dword v160, v[156:157], off
	v_lshl_add_u64 v[156:157], v[156:157], 0, s[6:7]
	global_load_dword v161, v[156:157], off
	v_lshl_add_u64 v[156:157], v[156:157], 0, s[6:7]
	global_load_dword v162, v[156:157], off
	v_lshl_add_u64 v[156:157], v[156:157], 0, s[6:7]
	global_load_dword v163, v[156:157], off
	v_lshl_add_u64 v[156:157], v[156:157], 0, s[6:7]
	global_load_dword v164, v[156:157], off
	v_lshl_add_u64 v[156:157], v[156:157], 0, s[6:7]
	global_load_dword v165, v[156:157], off
	v_lshl_add_u64 v[156:157], v[156:157], 0, s[6:7]
	global_load_dword v166, v[156:157], off
	v_lshl_add_u64 v[156:157], v[156:157], 0, s[6:7]
	global_load_dword v167, v[156:157], off
	v_lshl_add_u64 v[156:157], v[156:157], 0, s[6:7]
	global_load_dword v168, v[156:157], off
	v_lshl_add_u64 v[156:157], v[156:157], 0, s[6:7]
	global_load_dword v174, v[156:157], off
	v_lshl_add_u64 v[156:157], v[156:157], 0, s[6:7]
	global_load_dword v175, v[156:157], off
	v_lshl_add_u64 v[156:157], v[156:157], 0, s[6:7]
	global_load_dword v176, v[156:157], off
	v_lshl_add_u64 v[156:157], v[156:157], 0, s[6:7]
	global_load_dword v177, v[156:157], off
	v_lshl_add_u64 v[156:157], v[156:157], 0, s[6:7]
	global_load_dword v178, v[156:157], off
	v_lshl_add_u64 v[156:157], v[156:157], 0, s[6:7]
	global_load_dword v179, v[156:157], off
	v_lshl_add_u64 v[156:157], v[156:157], 0, s[6:7]
	global_load_dword v180, v[156:157], off
	v_lshl_add_u64 v[156:157], v[156:157], 0, s[6:7]
	global_load_dword v181, v[156:157], off
	v_lshl_add_u64 v[156:157], v[156:157], 0, s[6:7]
	global_load_dword v182, v[156:157], off
	v_lshl_add_u64 v[156:157], v[156:157], 0, s[6:7]
	global_load_dword v183, v[156:157], off
	v_lshl_add_u64 v[156:157], v[156:157], 0, s[6:7]
	global_load_dword v184, v[156:157], off
	v_lshl_add_u64 v[156:157], v[156:157], 0, s[6:7]
	global_load_dword v185, v[156:157], off
	v_lshl_add_u64 v[156:157], v[156:157], 0, s[6:7]
	global_load_dword v186, v[156:157], off
	v_lshl_add_u64 v[156:157], v[156:157], 0, s[6:7]
	global_load_dword v187, v[156:157], off
	v_lshl_add_u64 v[156:157], v[156:157], 0, s[6:7]
	global_load_dword v188, v[156:157], off
	v_lshl_add_u64 v[156:157], v[156:157], 0, s[6:7]
	global_load_dword v189, v[156:157], off
	v_lshl_add_u64 v[156:157], v[156:157], 0, s[6:7]
	global_load_dword v190, v[156:157], off
	v_lshl_add_u64 v[156:157], v[156:157], 0, s[6:7]
	global_load_dword v191, v[156:157], off
	v_lshl_add_u64 v[156:157], v[156:157], 0, s[6:7]
	global_load_dword v192, v[156:157], off
	v_lshl_add_u64 v[156:157], v[156:157], 0, s[6:7]
	global_load_dword v193, v[156:157], off
	v_lshl_add_u64 v[156:157], v[156:157], 0, s[6:7]
	global_load_dword v194, v[156:157], off
	v_lshl_add_u64 v[156:157], v[156:157], 0, s[6:7]
	global_load_dword v195, v[156:157], off
	v_lshl_add_u64 v[156:157], v[156:157], 0, s[6:7]
	global_load_dword v196, v[156:157], off
	v_lshl_add_u64 v[156:157], v[156:157], 0, s[6:7]
	global_load_dword v197, v[156:157], off
	v_lshl_add_u64 v[156:157], v[156:157], 0, s[6:7]
	global_load_dword v198, v[156:157], off
	v_lshl_add_u64 v[156:157], v[156:157], 0, s[6:7]
	global_load_dword v199, v[156:157], off
	v_lshl_add_u64 v[156:157], v[156:157], 0, s[6:7]
	global_load_dword v200, v[156:157], off
	v_lshl_add_u64 v[156:157], v[156:157], 0, s[6:7]
	global_load_dword v201, v[156:157], off
	v_lshl_add_u64 v[156:157], v[156:157], 0, s[6:7]
	global_load_dword v202, v[156:157], off
	v_lshl_add_u64 v[156:157], v[156:157], 0, s[6:7]
	global_load_dword v203, v[156:157], off
	v_lshl_add_u64 v[156:157], v[156:157], 0, s[6:7]
	global_load_dword v204, v[156:157], off
	v_lshl_add_u64 v[156:157], v[156:157], 0, s[6:7]
	global_load_dword v205, v[156:157], off
	v_lshl_add_u64 v[156:157], v[156:157], 0, s[6:7]
	global_load_dword v206, v[156:157], off
	v_lshl_add_u64 v[156:157], v[156:157], 0, s[6:7]
	global_load_dword v207, v[156:157], off
	v_lshl_add_u64 v[156:157], v[156:157], 0, s[6:7]
	global_load_dword v208, v[156:157], off
	v_lshl_add_u64 v[156:157], v[156:157], 0, s[6:7]
	global_load_dword v209, v[156:157], off
	v_lshl_add_u64 v[156:157], v[156:157], 0, s[6:7]
	global_load_dword v210, v[156:157], off
	v_lshl_add_u64 v[156:157], v[156:157], 0, s[6:7]
	v_add_u32_e32 v25, 0x400, v6
	ds_read2_b32 v[8:9], v6 offset1:65
	ds_read2_b32 v[10:11], v6 offset0:130 offset1:195
	ds_read2_b32 v[12:13], v25 offset0:4 offset1:69
	ds_read2_b32 v[14:15], v25 offset0:134 offset1:199
	v_add_u32_e32 v24, 0x820, v6
	v_add_u32_e32 v25, 0xc20, v6
	ds_read2_b32 v[16:17], v24 offset1:65
	ds_read2_b32 v[18:19], v24 offset0:130 offset1:195
	ds_read2_b32 v[20:21], v25 offset0:4 offset1:69
	ds_read2_b32 v[22:23], v25 offset0:134 offset1:199
	s_waitcnt vmcnt(32)
; __device__ __forceinline__ unsigned f2bf(float f) { return pk2(f, 0.f) & 0xffffu; }
; __device__ __forceinline__ void p0_transpose_item(const float* W, int K, int N, bf16* WT, float* scr, int item, int lane, const float* scale, const float* cb, float* c1, float* c2) {
;     ...
;     if (c1) { float a1 = 0.f, a2 = 0.f;
;         for (int kk = 0; kk < 64; ++kk) { a1 += __uint_as_float(f2bf(scr[kk * 65 + lane]) << 16); a2 += cb[k0 + kk] * W[(size_t)(k0 + kk) * N + n0 + lane]; }
	s_waitcnt lgkmcnt(4)
	v_cvt_pk_bf16_f32 v26, v8, v169
	v_readlane_b32 vcc_lo, v155, 0
	v_lshlrev_b32_e32 v26, 16, v26
	v_mul_f32_e32 v27, vcc_lo, v158
	v_add_f32_e32 v3, v3, v26
	v_add_f32_e32 v2, v2, v27
	v_cvt_pk_bf16_f32 v28, v9, v169
	v_readlane_b32 vcc_hi, v155, 1
	v_lshlrev_b32_e32 v28, 16, v28
	v_mul_f32_e32 v29, vcc_hi, v159
	v_add_f32_e32 v3, v3, v28
	v_add_f32_e32 v2, v2, v29
	v_cvt_pk_bf16_f32 v26, v10, v169
	v_readlane_b32 vcc_lo, v155, 2
	v_lshlrev_b32_e32 v26, 16, v26
	v_mul_f32_e32 v27, vcc_lo, v160
	v_add_f32_e32 v3, v3, v26
	v_add_f32_e32 v2, v2, v27
	v_cvt_pk_bf16_f32 v28, v11, v169
	v_readlane_b32 vcc_hi, v155, 3
	v_lshlrev_b32_e32 v28, 16, v28
	v_mul_f32_e32 v29, vcc_hi, v161
	v_add_f32_e32 v3, v3, v28
	v_add_f32_e32 v2, v2, v29
	v_cvt_pk_bf16_f32 v26, v12, v169
	v_readlane_b32 vcc_lo, v155, 4
	v_lshlrev_b32_e32 v26, 16, v26
	v_mul_f32_e32 v27, vcc_lo, v162
	v_add_f32_e32 v3, v3, v26
	v_add_f32_e32 v2, v2, v27
	v_cvt_pk_bf16_f32 v28, v13, v169
	v_readlane_b32 vcc_hi, v155, 5
	v_lshlrev_b32_e32 v28, 16, v28
	v_mul_f32_e32 v29, vcc_hi, v163
	v_add_f32_e32 v3, v3, v28
	v_add_f32_e32 v2, v2, v29
	v_cvt_pk_bf16_f32 v26, v14, v169
	v_readlane_b32 vcc_lo, v155, 6
	v_lshlrev_b32_e32 v26, 16, v26
	v_mul_f32_e32 v27, vcc_lo, v164
	v_add_f32_e32 v3, v3, v26
	v_add_f32_e32 v2, v2, v27
	v_cvt_pk_bf16_f32 v28, v15, v169
	v_readlane_b32 vcc_hi, v155, 7
	v_lshlrev_b32_e32 v28, 16, v28
	v_mul_f32_e32 v29, vcc_hi, v165
	v_add_f32_e32 v3, v3, v28
	v_add_f32_e32 v2, v2, v29
	v_add_u32_e32 v24, 0x1040, v6
	v_add_u32_e32 v25, 0x1440, v6
	ds_read2_b32 v[8:9], v24 offset1:65
	ds_read2_b32 v[10:11], v24 offset0:130 offset1:195
	ds_read2_b32 v[12:13], v25 offset0:4 offset1:69
	ds_read2_b32 v[14:15], v25 offset0:134 offset1:199
	s_waitcnt lgkmcnt(4)
	v_cvt_pk_bf16_f32 v26, v16, v169
	v_readlane_b32 vcc_lo, v155, 8
	v_lshlrev_b32_e32 v26, 16, v26
	v_mul_f32_e32 v27, vcc_lo, v166
	v_add_f32_e32 v3, v3, v26
	v_add_f32_e32 v2, v2, v27
	v_cvt_pk_bf16_f32 v28, v17, v169
	v_readlane_b32 vcc_hi, v155, 9
	v_lshlrev_b32_e32 v28, 16, v28
	v_mul_f32_e32 v29, vcc_hi, v167
	v_add_f32_e32 v3, v3, v28
	v_add_f32_e32 v2, v2, v29
	v_cvt_pk_bf16_f32 v26, v18, v169
	v_readlane_b32 vcc_lo, v155, 10
	v_lshlrev_b32_e32 v26, 16, v26
	v_mul_f32_e32 v27, vcc_lo, v168
	v_add_f32_e32 v3, v3, v26
	v_add_f32_e32 v2, v2, v27
	v_cvt_pk_bf16_f32 v28, v19, v169
	v_readlane_b32 vcc_hi, v155, 11
	v_lshlrev_b32_e32 v28, 16, v28
	v_mul_f32_e32 v29, vcc_hi, v174
	v_add_f32_e32 v3, v3, v28
	v_add_f32_e32 v2, v2, v29
	v_cvt_pk_bf16_f32 v26, v20, v169
	v_readlane_b32 vcc_lo, v155, 12
	v_lshlrev_b32_e32 v26, 16, v26
	v_mul_f32_e32 v27, vcc_lo, v175
	v_add_f32_e32 v3, v3, v26
	v_add_f32_e32 v2, v2, v27
	v_cvt_pk_bf16_f32 v28, v21, v169
	v_readlane_b32 vcc_hi, v155, 13
	v_lshlrev_b32_e32 v28, 16, v28
	v_mul_f32_e32 v29, vcc_hi, v176
	v_add_f32_e32 v3, v3, v28
	v_add_f32_e32 v2, v2, v29
	v_cvt_pk_bf16_f32 v26, v22, v169
	v_readlane_b32 vcc_lo, v155, 14
	v_lshlrev_b32_e32 v26, 16, v26
	v_mul_f32_e32 v27, vcc_lo, v177
	v_add_f32_e32 v3, v3, v26
	v_add_f32_e32 v2, v2, v27
	v_cvt_pk_bf16_f32 v28, v23, v169
	v_readlane_b32 vcc_hi, v155, 15
	v_lshlrev_b32_e32 v28, 16, v28
	v_mul_f32_e32 v29, vcc_hi, v178
	v_add_f32_e32 v3, v3, v28
	v_add_f32_e32 v2, v2, v29
	global_load_dword v211, v[156:157], off
	v_lshl_add_u64 v[156:157], v[156:157], 0, s[6:7]
	global_load_dword v212, v[156:157], off
	v_lshl_add_u64 v[156:157], v[156:157], 0, s[6:7]
	global_load_dword v213, v[156:157], off
	v_lshl_add_u64 v[156:157], v[156:157], 0, s[6:7]
	global_load_dword v224, v[156:157], off
	v_lshl_add_u64 v[156:157], v[156:157], 0, s[6:7]
	global_load_dword v225, v[156:157], off
	v_lshl_add_u64 v[156:157], v[156:157], 0, s[6:7]
	global_load_dword v226, v[156:157], off
	v_lshl_add_u64 v[156:157], v[156:157], 0, s[6:7]
	global_load_dword v227, v[156:157], off
	v_lshl_add_u64 v[156:157], v[156:157], 0, s[6:7]
	global_load_dword v228, v[156:157], off
	v_lshl_add_u64 v[156:157], v[156:157], 0, s[6:7]
	global_load_dword v229, v[156:157], off
	v_lshl_add_u64 v[156:157], v[156:157], 0, s[6:7]
	global_load_dword v230, v[156:157], off
	v_lshl_add_u64 v[156:157], v[156:157], 0, s[6:7]
	global_load_dword v231, v[156:157], off
	v_lshl_add_u64 v[156:157], v[156:157], 0, s[6:7]
	global_load_dword v232, v[156:157], off
	v_lshl_add_u64 v[156:157], v[156:157], 0, s[6:7]
	global_load_dword v233, v[156:157], off
	v_lshl_add_u64 v[156:157], v[156:157], 0, s[6:7]
	global_load_dword v234, v[156:157], off
	v_lshl_add_u64 v[156:157], v[156:157], 0, s[6:7]
	global_load_dword v235, v[156:157], off
	v_lshl_add_u64 v[156:157], v[156:157], 0, s[6:7]
	global_load_dword v236, v[156:157], off
	v_lshl_add_u64 v[156:157], v[156:157], 0, s[6:7]
	v_add_u32_e32 v24, 0x1860, v6
	v_add_u32_e32 v25, 0x1c60, v6
	ds_read2_b32 v[16:17], v24 offset1:65
	ds_read2_b32 v[18:19], v24 offset0:130 offset1:195
	ds_read2_b32 v[20:21], v25 offset0:4 offset1:69
	ds_read2_b32 v[22:23], v25 offset0:134 offset1:199
	s_waitcnt vmcnt(32)
	s_waitcnt lgkmcnt(4)
; __device__ __forceinline__ unsigned f2bf(float f) { return pk2(f, 0.f) & 0xffffu; }
; __device__ __forceinline__ void p0_transpose_item(const float* W, int K, int N, bf16* WT, float* scr, int item, int lane, const float* scale, const float* cb, float* c1, float* c2) {
;     ...
;     if (c1) { float a1 = 0.f, a2 = 0.f;
;         for (int kk = 0; kk < 64; ++kk) { a1 += __uint_as_float(f2bf(scr[kk * 65 + lane]) << 16); a2 += cb[k0 + kk] * W[(size_t)(k0 + kk) * N + n0 + lane]; }
	v_cvt_pk_bf16_f32 v26, v8, v169
	v_readlane_b32 vcc_lo, v155, 16
	v_lshlrev_b32_e32 v26, 16, v26
	v_mul_f32_e32 v27, vcc_lo, v179
	v_add_f32_e32 v3, v3, v26
	v_add_f32_e32 v2, v2, v27
	v_cvt_pk_bf16_f32 v28, v9, v169
	v_readlane_b32 vcc_hi, v155, 17
	v_lshlrev_b32_e32 v28, 16, v28
	v_mul_f32_e32 v29, vcc_hi, v180
	v_add_f32_e32 v3, v3, v28
	v_add_f32_e32 v2, v2, v29
	v_cvt_pk_bf16_f32 v26, v10, v169
	v_readlane_b32 vcc_lo, v155, 18
	v_lshlrev_b32_e32 v26, 16, v26
	v_mul_f32_e32 v27, vcc_lo, v181
	v_add_f32_e32 v3, v3, v26
	v_add_f32_e32 v2, v2, v27
	v_cvt_pk_bf16_f32 v28, v11, v169
	v_readlane_b32 vcc_hi, v155, 19
	v_lshlrev_b32_e32 v28, 16, v28
	v_mul_f32_e32 v29, vcc_hi, v182
	v_add_f32_e32 v3, v3, v28
	v_add_f32_e32 v2, v2, v29
	v_cvt_pk_bf16_f32 v26, v12, v169
	v_readlane_b32 vcc_lo, v155, 20
	v_lshlrev_b32_e32 v26, 16, v26
	v_mul_f32_e32 v27, vcc_lo, v183
	v_add_f32_e32 v3, v3, v26
	v_add_f32_e32 v2, v2, v27
	v_cvt_pk_bf16_f32 v28, v13, v169
	v_readlane_b32 vcc_hi, v155, 21
	v_lshlrev_b32_e32 v28, 16, v28
	v_mul_f32_e32 v29, vcc_hi, v184
	v_add_f32_e32 v3, v3, v28
	v_add_f32_e32 v2, v2, v29
	v_cvt_pk_bf16_f32 v26, v14, v169
	v_readlane_b32 vcc_lo, v155, 22
	v_lshlrev_b32_e32 v26, 16, v26
	v_mul_f32_e32 v27, vcc_lo, v185
	v_add_f32_e32 v3, v3, v26
	v_add_f32_e32 v2, v2, v27
	v_cvt_pk_bf16_f32 v28, v15, v169
	v_readlane_b32 vcc_hi, v155, 23
	v_lshlrev_b32_e32 v28, 16, v28
	v_mul_f32_e32 v29, vcc_hi, v186
	v_add_f32_e32 v3, v3, v28
	v_add_f32_e32 v2, v2, v29
	v_add_u32_e32 v24, 0x2080, v6
	v_add_u32_e32 v25, 0x2480, v6
	ds_read2_b32 v[8:9], v24 offset1:65
	ds_read2_b32 v[10:11], v24 offset0:130 offset1:195
	ds_read2_b32 v[12:13], v25 offset0:4 offset1:69
	ds_read2_b32 v[14:15], v25 offset0:134 offset1:199
	s_waitcnt lgkmcnt(4)
	v_cvt_pk_bf16_f32 v26, v16, v169
	v_readlane_b32 vcc_lo, v155, 24
	v_lshlrev_b32_e32 v26, 16, v26
	v_mul_f32_e32 v27, vcc_lo, v187
	v_add_f32_e32 v3, v3, v26
	v_add_f32_e32 v2, v2, v27
	v_cvt_pk_bf16_f32 v28, v17, v169
	v_readlane_b32 vcc_hi, v155, 25
	v_lshlrev_b32_e32 v28, 16, v28
	v_mul_f32_e32 v29, vcc_hi, v188
	v_add_f32_e32 v3, v3, v28
	v_add_f32_e32 v2, v2, v29
	v_cvt_pk_bf16_f32 v26, v18, v169
	v_readlane_b32 vcc_lo, v155, 26
	v_lshlrev_b32_e32 v26, 16, v26
	v_mul_f32_e32 v27, vcc_lo, v189
	v_add_f32_e32 v3, v3, v26
	v_add_f32_e32 v2, v2, v27
	v_cvt_pk_bf16_f32 v28, v19, v169
	v_readlane_b32 vcc_hi, v155, 27
	v_lshlrev_b32_e32 v28, 16, v28
	v_mul_f32_e32 v29, vcc_hi, v190
	v_add_f32_e32 v3, v3, v28
	v_add_f32_e32 v2, v2, v29
	v_cvt_pk_bf16_f32 v26, v20, v169
	v_readlane_b32 vcc_lo, v155, 28
	v_lshlrev_b32_e32 v26, 16, v26
	v_mul_f32_e32 v27, vcc_lo, v191
	v_add_f32_e32 v3, v3, v26
	v_add_f32_e32 v2, v2, v27
	v_cvt_pk_bf16_f32 v28, v21, v169
	v_readlane_b32 vcc_hi, v155, 29
	v_lshlrev_b32_e32 v28, 16, v28
	v_mul_f32_e32 v29, vcc_hi, v192
	v_add_f32_e32 v3, v3, v28
	v_add_f32_e32 v2, v2, v29
	v_cvt_pk_bf16_f32 v26, v22, v169
	v_readlane_b32 vcc_lo, v155, 30
	v_lshlrev_b32_e32 v26, 16, v26
	v_mul_f32_e32 v27, vcc_lo, v193
	v_add_f32_e32 v3, v3, v26
	v_add_f32_e32 v2, v2, v27
	v_cvt_pk_bf16_f32 v28, v23, v169
	v_readlane_b32 vcc_hi, v155, 31
	v_lshlrev_b32_e32 v28, 16, v28
	v_mul_f32_e32 v29, vcc_hi, v194
	v_add_f32_e32 v3, v3, v28
	v_add_f32_e32 v2, v2, v29
	v_add_u32_e32 v24, 0x28a0, v6
	v_add_u32_e32 v25, 0x2ca0, v6
	ds_read2_b32 v[16:17], v24 offset1:65
	ds_read2_b32 v[18:19], v24 offset0:130 offset1:195
	ds_read2_b32 v[20:21], v25 offset0:4 offset1:69
	ds_read2_b32 v[22:23], v25 offset0:134 offset1:199
	s_waitcnt vmcnt(16)
	s_waitcnt lgkmcnt(4)
	v_cvt_pk_bf16_f32 v26, v8, v169
	v_readlane_b32 vcc_lo, v155, 32
	v_lshlrev_b32_e32 v26, 16, v26
	v_mul_f32_e32 v27, vcc_lo, v195
	v_add_f32_e32 v3, v3, v26
	v_add_f32_e32 v2, v2, v27
	v_cvt_pk_bf16_f32 v28, v9, v169
	v_readlane_b32 vcc_hi, v155, 33
	v_lshlrev_b32_e32 v28, 16, v28
	v_mul_f32_e32 v29, vcc_hi, v196
	v_add_f32_e32 v3, v3, v28
	v_add_f32_e32 v2, v2, v29
	v_cvt_pk_bf16_f32 v26, v10, v169
	v_readlane_b32 vcc_lo, v155, 34
	v_lshlrev_b32_e32 v26, 16, v26
	v_mul_f32_e32 v27, vcc_lo, v197
	v_add_f32_e32 v3, v3, v26
	v_add_f32_e32 v2, v2, v27
	v_cvt_pk_bf16_f32 v28, v11, v169
	v_readlane_b32 vcc_hi, v155, 35
	v_lshlrev_b32_e32 v28, 16, v28
	v_mul_f32_e32 v29, vcc_hi, v198
	v_add_f32_e32 v3, v3, v28
	v_add_f32_e32 v2, v2, v29
	v_cvt_pk_bf16_f32 v26, v12, v169
	v_readlane_b32 vcc_lo, v155, 36
	v_lshlrev_b32_e32 v26, 16, v26
	v_mul_f32_e32 v27, vcc_lo, v199
	v_add_f32_e32 v3, v3, v26
	v_add_f32_e32 v2, v2, v27
	v_cvt_pk_bf16_f32 v28, v13, v169
	v_readlane_b32 vcc_hi, v155, 37
	v_lshlrev_b32_e32 v28, 16, v28
	v_mul_f32_e32 v29, vcc_hi, v200
	v_add_f32_e32 v3, v3, v28
	v_add_f32_e32 v2, v2, v29
	v_cvt_pk_bf16_f32 v26, v14, v169
	v_readlane_b32 vcc_lo, v155, 38
	v_lshlrev_b32_e32 v26, 16, v26
	v_mul_f32_e32 v27, vcc_lo, v201
	v_add_f32_e32 v3, v3, v26
	v_add_f32_e32 v2, v2, v27
	v_cvt_pk_bf16_f32 v28, v15, v169
	v_readlane_b32 vcc_hi, v155, 39
	v_lshlrev_b32_e32 v28, 16, v28
	v_mul_f32_e32 v29, vcc_hi, v202
	v_add_f32_e32 v3, v3, v28
	v_add_f32_e32 v2, v2, v29
	v_add_u32_e32 v24, 0x30c0, v6
	v_add_u32_e32 v25, 0x34c0, v6
	ds_read2_b32 v[8:9], v24 offset1:65
	ds_read2_b32 v[10:11], v24 offset0:130 offset1:195
	ds_read2_b32 v[12:13], v25 offset0:4 offset1:69
	ds_read2_b32 v[14:15], v25 offset0:134 offset1:199
	s_waitcnt lgkmcnt(4)
; __device__ __forceinline__ unsigned f2bf(float f) { return pk2(f, 0.f) & 0xffffu; }
; __device__ __forceinline__ void p0_transpose_item(const float* W, int K, int N, bf16* WT, float* scr, int item, int lane, const float* scale, const float* cb, float* c1, float* c2) {
;     ...
;     if (c1) { float a1 = 0.f, a2 = 0.f;
;         for (int kk = 0; kk < 64; ++kk) { a1 += __uint_as_float(f2bf(scr[kk * 65 + lane]) << 16); a2 += cb[k0 + kk] * W[(size_t)(k0 + kk) * N + n0 + lane]; }
;         atomicAdd(c1 + n0 + lane, a1); atomicAdd(c2 + n0 + lane, a2); }
	v_cvt_pk_bf16_f32 v26, v16, v169
	v_readlane_b32 vcc_lo, v155, 40
	v_lshlrev_b32_e32 v26, 16, v26
	v_mul_f32_e32 v27, vcc_lo, v203
	v_add_f32_e32 v3, v3, v26
	v_add_f32_e32 v2, v2, v27
	v_cvt_pk_bf16_f32 v28, v17, v169
	v_readlane_b32 vcc_hi, v155, 41
	v_lshlrev_b32_e32 v28, 16, v28
	v_mul_f32_e32 v29, vcc_hi, v204
	v_add_f32_e32 v3, v3, v28
	v_add_f32_e32 v2, v2, v29
	v_cvt_pk_bf16_f32 v26, v18, v169
	v_readlane_b32 vcc_lo, v155, 42
	v_lshlrev_b32_e32 v26, 16, v26
	v_mul_f32_e32 v27, vcc_lo, v205
	v_add_f32_e32 v3, v3, v26
	v_add_f32_e32 v2, v2, v27
	v_cvt_pk_bf16_f32 v28, v19, v169
	v_readlane_b32 vcc_hi, v155, 43
	v_lshlrev_b32_e32 v28, 16, v28
	v_mul_f32_e32 v29, vcc_hi, v206
	v_add_f32_e32 v3, v3, v28
	v_add_f32_e32 v2, v2, v29
	v_cvt_pk_bf16_f32 v26, v20, v169
	v_readlane_b32 vcc_lo, v155, 44
	v_lshlrev_b32_e32 v26, 16, v26
	v_mul_f32_e32 v27, vcc_lo, v207
	v_add_f32_e32 v3, v3, v26
	v_add_f32_e32 v2, v2, v27
	v_cvt_pk_bf16_f32 v28, v21, v169
	v_readlane_b32 vcc_hi, v155, 45
	v_lshlrev_b32_e32 v28, 16, v28
	v_mul_f32_e32 v29, vcc_hi, v208
	v_add_f32_e32 v3, v3, v28
	v_add_f32_e32 v2, v2, v29
	v_cvt_pk_bf16_f32 v26, v22, v169
	v_readlane_b32 vcc_lo, v155, 46
	v_lshlrev_b32_e32 v26, 16, v26
	v_mul_f32_e32 v27, vcc_lo, v209
	v_add_f32_e32 v3, v3, v26
	v_add_f32_e32 v2, v2, v27
	v_cvt_pk_bf16_f32 v28, v23, v169
	v_readlane_b32 vcc_hi, v155, 47
	v_lshlrev_b32_e32 v28, 16, v28
	v_mul_f32_e32 v29, vcc_hi, v210
	v_add_f32_e32 v3, v3, v28
	v_add_f32_e32 v2, v2, v29
	v_add_u32_e32 v24, 0x38e0, v6
	v_add_u32_e32 v25, 0x3ce0, v6
	ds_read2_b32 v[16:17], v24 offset1:65
	ds_read2_b32 v[18:19], v24 offset0:130 offset1:195
	ds_read2_b32 v[20:21], v25 offset0:4 offset1:69
	ds_read2_b32 v[22:23], v25 offset0:134 offset1:199
	s_waitcnt vmcnt(0)
	s_waitcnt lgkmcnt(4)
	v_cvt_pk_bf16_f32 v26, v8, v169
	v_readlane_b32 vcc_lo, v155, 48
	v_lshlrev_b32_e32 v26, 16, v26
	v_mul_f32_e32 v27, vcc_lo, v211
	v_add_f32_e32 v3, v3, v26
	v_add_f32_e32 v2, v2, v27
	v_cvt_pk_bf16_f32 v28, v9, v169
	v_readlane_b32 vcc_hi, v155, 49
	v_lshlrev_b32_e32 v28, 16, v28
	v_mul_f32_e32 v29, vcc_hi, v212
	v_add_f32_e32 v3, v3, v28
	v_add_f32_e32 v2, v2, v29
	v_cvt_pk_bf16_f32 v26, v10, v169
	v_readlane_b32 vcc_lo, v155, 50
	v_lshlrev_b32_e32 v26, 16, v26
	v_mul_f32_e32 v27, vcc_lo, v213
	v_add_f32_e32 v3, v3, v26
	v_add_f32_e32 v2, v2, v27
	v_cvt_pk_bf16_f32 v28, v11, v169
	v_readlane_b32 vcc_hi, v155, 51
	v_lshlrev_b32_e32 v28, 16, v28
	v_mul_f32_e32 v29, vcc_hi, v224
	v_add_f32_e32 v3, v3, v28
	v_add_f32_e32 v2, v2, v29
	v_cvt_pk_bf16_f32 v26, v12, v169
	v_readlane_b32 vcc_lo, v155, 52
	v_lshlrev_b32_e32 v26, 16, v26
	v_mul_f32_e32 v27, vcc_lo, v225
	v_add_f32_e32 v3, v3, v26
	v_add_f32_e32 v2, v2, v27
	v_cvt_pk_bf16_f32 v28, v13, v169
	v_readlane_b32 vcc_hi, v155, 53
	v_lshlrev_b32_e32 v28, 16, v28
	v_mul_f32_e32 v29, vcc_hi, v226
	v_add_f32_e32 v3, v3, v28
	v_add_f32_e32 v2, v2, v29
	v_cvt_pk_bf16_f32 v26, v14, v169
	v_readlane_b32 vcc_lo, v155, 54
	v_lshlrev_b32_e32 v26, 16, v26
	v_mul_f32_e32 v27, vcc_lo, v227
	v_add_f32_e32 v3, v3, v26
	v_add_f32_e32 v2, v2, v27
	v_cvt_pk_bf16_f32 v28, v15, v169
	v_readlane_b32 vcc_hi, v155, 55
	v_lshlrev_b32_e32 v28, 16, v28
	v_mul_f32_e32 v29, vcc_hi, v228
	v_add_f32_e32 v3, v3, v28
	v_add_f32_e32 v2, v2, v29
	s_waitcnt lgkmcnt(0)
	v_cvt_pk_bf16_f32 v26, v16, v169
	v_readlane_b32 vcc_lo, v155, 56
	v_lshlrev_b32_e32 v26, 16, v26
	v_mul_f32_e32 v27, vcc_lo, v229
	v_add_f32_e32 v3, v3, v26
	v_add_f32_e32 v2, v2, v27
	v_cvt_pk_bf16_f32 v28, v17, v169
	v_readlane_b32 vcc_hi, v155, 57
	v_lshlrev_b32_e32 v28, 16, v28
	v_mul_f32_e32 v29, vcc_hi, v230
	v_add_f32_e32 v3, v3, v28
	v_add_f32_e32 v2, v2, v29
	v_cvt_pk_bf16_f32 v26, v18, v169
	v_readlane_b32 vcc_lo, v155, 58
	v_lshlrev_b32_e32 v26, 16, v26
	v_mul_f32_e32 v27, vcc_lo, v231
	v_add_f32_e32 v3, v3, v26
	v_add_f32_e32 v2, v2, v27
	v_cvt_pk_bf16_f32 v28, v19, v169
	v_readlane_b32 vcc_hi, v155, 59
	v_lshlrev_b32_e32 v28, 16, v28
	v_mul_f32_e32 v29, vcc_hi, v232
	v_add_f32_e32 v3, v3, v28
	v_add_f32_e32 v2, v2, v29
	v_cvt_pk_bf16_f32 v26, v20, v169
	v_readlane_b32 vcc_lo, v155, 60
	v_lshlrev_b32_e32 v26, 16, v26
	v_mul_f32_e32 v27, vcc_lo, v233
	v_add_f32_e32 v3, v3, v26
	v_add_f32_e32 v2, v2, v27
	v_cvt_pk_bf16_f32 v28, v21, v169
	v_readlane_b32 vcc_hi, v155, 61
	v_lshlrev_b32_e32 v28, 16, v28
	v_mul_f32_e32 v29, vcc_hi, v234
	v_add_f32_e32 v3, v3, v28
	v_add_f32_e32 v2, v2, v29
	v_cvt_pk_bf16_f32 v26, v22, v169
	v_readlane_b32 vcc_lo, v155, 62
	v_lshlrev_b32_e32 v26, 16, v26
	v_mul_f32_e32 v27, vcc_lo, v235
	v_add_f32_e32 v3, v3, v26
	v_add_f32_e32 v2, v2, v27
	v_cvt_pk_bf16_f32 v28, v23, v169
	v_readlane_b32 vcc_hi, v155, 63
	v_lshlrev_b32_e32 v28, 16, v28
	v_mul_f32_e32 v29, vcc_hi, v236
	v_add_f32_e32 v3, v3, v28
	v_add_f32_e32 v2, v2, v29
	s_add_u32 s1, s40, s2
	s_addc_u32 s4, s41, s3
	s_add_u32 s5, s42, s2
	s_addc_u32 s6, s43, s3
	s_add_u32 s2, s1, s45
	s_addc_u32 s3, s4, 0
	v_mov_b32_e32 v75, v169
	v_lshl_add_u64 v[0:1], s[2:3], 0, v[74:75]
	s_add_u32 s2, s5, s45
	s_addc_u32 s3, s6, 0
	global_atomic_add_f32 v[0:1], v3, off
	v_lshl_add_u64 v[0:1], s[2:3], 0, v[74:75]
	global_atomic_add_f32 v[0:1], v2, off
	s_waitcnt lgkmcnt(0)
